# GEMM K-loops (FFN-in, FFN-out, mixer-in, mixer-out): when a unit has no successor the last iteration runs from a copy without the 14 next-tile LDS-DMA prefetches (no dummy reloads of the finished tile
# baseline (speedup 1.0000x reference)
.LBB0_345:
	s_cmp_lg_u32 s58, 12
	s_cbranch_scc1 .Lpfi_body
	s_cmp_eq_u32 s0, 0
	s_cbranch_scc1 .Lpfi_tail
.Lpfi_body:
	s_add_u32 s42, s56, 0xfffc0080
	s_addc_u32 s43, s57, -1
	s_add_i32 s59, 0, 0x10000
	s_cmp_eq_u32 s58, 12
	s_cselect_b32 s55, s17, s43
	s_cselect_b32 s54, s19, s42
	v_add_u32_e32 v138, s59, v141
	s_cselect_b32 s43, s15, s53
	s_cselect_b32 s42, s50, s51
	s_add_i32 s62, 0, 0x14000
	ds_read_b128 v[154:157], v138
	ds_read_b128 v[158:161], v138 offset:1024
	ds_read_b128 v[162:165], v138 offset:2048
	ds_read_b128 v[166:169], v138 offset:3072
	v_add_u32_e32 v138, s62, v141
	ds_read_b128 v[170:173], v138
	ds_read_b128 v[174:177], v138 offset:1024
	ds_read_b128 v[178:181], v138 offset:2048
	ds_read_b128 v[204:207], v138 offset:3072
	v_lshl_add_u64 v[138:139], s[56:57], 0, v[134:135]
	s_add_i32 m0, s38, 0xc000
	ds_read_b128 v[208:211], v143
	ds_read_b128 v[212:215], v143 offset:1024
	ds_read_b128 v[216:219], v143 offset:2048
	ds_read_b128 v[220:223], v143 offset:3072
	ds_read_b128 v[224:227], v143 offset:4096
	ds_read_b128 v[228:231], v143 offset:5120
	ds_read_b128 v[232:235], v143 offset:6144
	ds_read_b128 v[236:239], v143 offset:7168
	global_load_lds_dwordx4 v[138:139], off
	v_lshl_add_u64 v[138:139], s[56:57], 0, v[136:137]
	s_add_i32 m0, s38, 0xe000
	s_nop 0
	global_load_lds_dwordx4 v[138:139], off
	s_waitcnt vmcnt(8)
	s_waitcnt lgkmcnt(0)
	s_barrier
	s_setprio 1
	s_waitcnt lgkmcnt(0)
	v_mfma_f32_16x16x32_bf16 v[124:127], v[154:157], v[208:211], v[124:127]
	v_mfma_f32_16x16x32_bf16 v[116:119], v[162:165], v[208:211], v[116:119]
	v_mfma_f32_16x16x32_bf16 v[108:111], v[154:157], v[216:219], v[108:111]
	v_mfma_f32_16x16x32_bf16 v[100:103], v[162:165], v[216:219], v[100:103]
	v_mfma_f32_16x16x32_bf16 v[92:95], v[154:157], v[224:227], v[92:95]
	v_mfma_f32_16x16x32_bf16 v[84:87], v[162:165], v[224:227], v[84:87]
	v_mfma_f32_16x16x32_bf16 v[76:79], v[154:157], v[232:235], v[76:79]
	v_mfma_f32_16x16x32_bf16 v[68:71], v[162:165], v[232:235], v[68:71]
	v_mfma_f32_16x16x32_bf16 v[124:127], v[158:161], v[212:215], v[124:127]
	v_mfma_f32_16x16x32_bf16 v[116:119], v[166:169], v[212:215], v[116:119]
	v_mfma_f32_16x16x32_bf16 v[108:111], v[158:161], v[220:223], v[108:111]
	v_mfma_f32_16x16x32_bf16 v[100:103], v[166:169], v[220:223], v[100:103]
	v_mfma_f32_16x16x32_bf16 v[92:95], v[158:161], v[228:231], v[92:95]
	v_mfma_f32_16x16x32_bf16 v[84:87], v[166:169], v[228:231], v[84:87]
	v_mfma_f32_16x16x32_bf16 v[76:79], v[158:161], v[236:239], v[76:79]
	v_mfma_f32_16x16x32_bf16 v[68:71], v[166:169], v[236:239], v[68:71]
	s_setprio 0
	s_setprio 1
	v_mfma_f32_16x16x32_bf16 v[120:123], v[170:173], v[208:211], v[120:123]
	v_mfma_f32_16x16x32_bf16 v[112:115], v[178:181], v[208:211], v[112:115]
	v_mfma_f32_16x16x32_bf16 v[104:107], v[170:173], v[216:219], v[104:107]
	v_mfma_f32_16x16x32_bf16 v[96:99], v[178:181], v[216:219], v[96:99]
	v_mfma_f32_16x16x32_bf16 v[88:91], v[170:173], v[224:227], v[88:91]
	v_mfma_f32_16x16x32_bf16 v[80:83], v[178:181], v[224:227], v[80:83]
	v_mfma_f32_16x16x32_bf16 v[72:75], v[170:173], v[232:235], v[72:75]
	v_mfma_f32_16x16x32_bf16 v[64:67], v[178:181], v[232:235], v[64:67]
	v_mfma_f32_16x16x32_bf16 v[120:123], v[174:177], v[212:215], v[120:123]
	v_mfma_f32_16x16x32_bf16 v[112:115], v[204:207], v[212:215], v[112:115]
	v_mfma_f32_16x16x32_bf16 v[104:107], v[174:177], v[220:223], v[104:107]
	v_mfma_f32_16x16x32_bf16 v[96:99], v[204:207], v[220:223], v[96:99]
	v_mfma_f32_16x16x32_bf16 v[88:91], v[174:177], v[228:231], v[88:91]
	v_mfma_f32_16x16x32_bf16 v[80:83], v[204:207], v[228:231], v[80:83]
	v_mfma_f32_16x16x32_bf16 v[72:75], v[174:177], v[236:239], v[72:75]
	v_mfma_f32_16x16x32_bf16 v[64:67], v[204:207], v[236:239], v[64:67]
	s_setprio 0
	s_barrier
	s_add_i32 s59, s59, s36
	v_lshl_add_u64 v[138:139], s[42:43], 0, v[144:145]
	s_mov_b32 m0, s59
	ds_read_b128 v[208:211], v143 offset:16384
	ds_read_b128 v[212:215], v143 offset:17408
	ds_read_b128 v[216:219], v143 offset:18432
	ds_read_b128 v[220:223], v143 offset:19456
	ds_read_b128 v[224:227], v143 offset:20480
	ds_read_b128 v[228:231], v143 offset:21504
	ds_read_b128 v[232:235], v143 offset:22528
	ds_read_b128 v[236:239], v143 offset:23552
	global_load_lds_dwordx4 v[138:139], off
	s_add_i32 m0, s59, 0x2000
	s_add_u32 s60, s42, 0x40000
	v_lshl_add_u64 v[240:241], s[42:43], 0, v[128:129]
	s_addc_u32 s61, s43, 0
	s_add_i32 s59, s62, s36
	global_load_lds_dwordx4 v[240:241], off
	v_lshl_add_u64 v[242:243], s[60:61], 0, v[144:145]
	s_mov_b32 m0, s59
	v_lshl_add_u64 v[244:245], s[54:55], 0, v[130:131]
	global_load_lds_dwordx4 v[242:243], off
	v_lshl_add_u64 v[242:243], s[60:61], 0, v[128:129]
	s_add_i32 m0, s59, 0x2000
	s_nop 0
	global_load_lds_dwordx4 v[242:243], off
	v_lshl_add_u64 v[242:243], s[54:55], 0, v[132:133]
	s_mov_b32 m0, s38
	s_nop 0
	global_load_lds_dwordx4 v[242:243], off
	s_mov_b32 m0, s40
	s_nop 0
	global_load_lds_dwordx4 v[244:245], off
	s_waitcnt vmcnt(8)
	s_waitcnt lgkmcnt(0)
	s_barrier
	s_setprio 1
	s_waitcnt lgkmcnt(0)
	v_mfma_f32_16x16x32_bf16 v[60:63], v[154:157], v[208:211], v[60:63]
	v_mfma_f32_16x16x32_bf16 v[52:55], v[162:165], v[208:211], v[52:55]
	v_mfma_f32_16x16x32_bf16 v[44:47], v[154:157], v[216:219], v[44:47]
	v_mfma_f32_16x16x32_bf16 v[36:39], v[162:165], v[216:219], v[36:39]
	v_mfma_f32_16x16x32_bf16 v[28:31], v[154:157], v[224:227], v[28:31]
	v_mfma_f32_16x16x32_bf16 v[20:23], v[162:165], v[224:227], v[20:23]
	v_mfma_f32_16x16x32_bf16 v[12:15], v[154:157], v[232:235], v[12:15]
	v_mfma_f32_16x16x32_bf16 v[4:7], v[162:165], v[232:235], v[4:7]
	v_mfma_f32_16x16x32_bf16 v[60:63], v[158:161], v[212:215], v[60:63]
	v_mfma_f32_16x16x32_bf16 v[52:55], v[166:169], v[212:215], v[52:55]
	v_mfma_f32_16x16x32_bf16 v[44:47], v[158:161], v[220:223], v[44:47]
	v_mfma_f32_16x16x32_bf16 v[36:39], v[166:169], v[220:223], v[36:39]
	v_mfma_f32_16x16x32_bf16 v[28:31], v[158:161], v[228:231], v[28:31]
	v_mfma_f32_16x16x32_bf16 v[20:23], v[166:169], v[228:231], v[20:23]
	v_mfma_f32_16x16x32_bf16 v[12:15], v[158:161], v[236:239], v[12:15]
	v_mfma_f32_16x16x32_bf16 v[4:7], v[166:169], v[236:239], v[4:7]
	s_setprio 0
	s_setprio 1
	v_mfma_f32_16x16x32_bf16 v[56:59], v[170:173], v[208:211], v[56:59]
	v_mfma_f32_16x16x32_bf16 v[48:51], v[178:181], v[208:211], v[48:51]
	v_mfma_f32_16x16x32_bf16 v[40:43], v[170:173], v[216:219], v[40:43]
	v_mfma_f32_16x16x32_bf16 v[32:35], v[178:181], v[216:219], v[32:35]
	v_mfma_f32_16x16x32_bf16 v[24:27], v[170:173], v[224:227], v[24:27]
	v_mfma_f32_16x16x32_bf16 v[16:19], v[178:181], v[224:227], v[16:19]
	v_mfma_f32_16x16x32_bf16 v[8:11], v[170:173], v[232:235], v[8:11]
	v_mfma_f32_16x16x32_bf16 v[0:3], v[178:181], v[232:235], v[0:3]
	v_mfma_f32_16x16x32_bf16 v[56:59], v[174:177], v[212:215], v[56:59]
	v_mfma_f32_16x16x32_bf16 v[48:51], v[204:207], v[212:215], v[48:51]
	v_mfma_f32_16x16x32_bf16 v[40:43], v[174:177], v[220:223], v[40:43]
	v_mfma_f32_16x16x32_bf16 v[32:35], v[204:207], v[220:223], v[32:35]
	v_mfma_f32_16x16x32_bf16 v[24:27], v[174:177], v[228:231], v[24:27]
	v_mfma_f32_16x16x32_bf16 v[16:19], v[204:207], v[228:231], v[16:19]
	v_mfma_f32_16x16x32_bf16 v[8:11], v[174:177], v[236:239], v[8:11]
	v_mfma_f32_16x16x32_bf16 v[0:3], v[204:207], v[236:239], v[0:3]
	s_setprio 0
	s_barrier
	s_add_i32 s59, 0, 0x18000
	s_add_i32 s60, 0, 0x1c000
	v_add_u32_e32 v166, s59, v141
	v_add_u32_e32 v190, s60, v141
	ds_read_b128 v[154:157], v166
	ds_read_b128 v[158:161], v166 offset:1024
	ds_read_b128 v[162:165], v166 offset:2048
	ds_read_b128 v[166:169], v166 offset:3072
	ds_read_b128 v[170:173], v190
	ds_read_b128 v[174:177], v190 offset:1024
	ds_read_b128 v[178:181], v190 offset:2048
	ds_read_b128 v[204:207], v190 offset:3072
	s_add_u32 s54, s54, 0x40000
	s_addc_u32 s55, s55, 0
	s_mov_b32 m0, s41
	v_lshl_add_u64 v[246:247], s[54:55], 0, v[132:133]
	ds_read_b128 v[208:211], v143 offset:32768
	ds_read_b128 v[212:215], v143 offset:33792
	ds_read_b128 v[216:219], v143 offset:34816
	ds_read_b128 v[220:223], v143 offset:35840
	ds_read_b128 v[224:227], v143 offset:36864
	ds_read_b128 v[228:231], v143 offset:37888
	ds_read_b128 v[232:235], v143 offset:38912
	ds_read_b128 v[236:239], v143 offset:39936
	global_load_lds_dwordx4 v[246:247], off
	v_lshl_add_u64 v[246:247], s[54:55], 0, v[130:131]
	s_mov_b32 m0, s44
	s_nop 0
	global_load_lds_dwordx4 v[246:247], off
	s_waitcnt vmcnt(8)
	s_waitcnt lgkmcnt(0)
	s_barrier
	s_setprio 1
	s_waitcnt lgkmcnt(0)
	v_mfma_f32_16x16x32_bf16 v[124:127], v[154:157], v[208:211], v[124:127]
	v_mfma_f32_16x16x32_bf16 v[116:119], v[162:165], v[208:211], v[116:119]
	v_mfma_f32_16x16x32_bf16 v[108:111], v[154:157], v[216:219], v[108:111]
	v_mfma_f32_16x16x32_bf16 v[100:103], v[162:165], v[216:219], v[100:103]
	v_mfma_f32_16x16x32_bf16 v[92:95], v[154:157], v[224:227], v[92:95]
	v_mfma_f32_16x16x32_bf16 v[84:87], v[162:165], v[224:227], v[84:87]
	v_mfma_f32_16x16x32_bf16 v[76:79], v[154:157], v[232:235], v[76:79]
	v_mfma_f32_16x16x32_bf16 v[68:71], v[162:165], v[232:235], v[68:71]
	v_mfma_f32_16x16x32_bf16 v[124:127], v[158:161], v[212:215], v[124:127]
	v_mfma_f32_16x16x32_bf16 v[116:119], v[166:169], v[212:215], v[116:119]
	v_mfma_f32_16x16x32_bf16 v[108:111], v[158:161], v[220:223], v[108:111]
	v_mfma_f32_16x16x32_bf16 v[100:103], v[166:169], v[220:223], v[100:103]
	v_mfma_f32_16x16x32_bf16 v[92:95], v[158:161], v[228:231], v[92:95]
	v_mfma_f32_16x16x32_bf16 v[84:87], v[166:169], v[228:231], v[84:87]
	v_mfma_f32_16x16x32_bf16 v[76:79], v[158:161], v[236:239], v[76:79]
	v_mfma_f32_16x16x32_bf16 v[68:71], v[166:169], v[236:239], v[68:71]
	s_setprio 0
	s_setprio 1
	v_mfma_f32_16x16x32_bf16 v[120:123], v[170:173], v[208:211], v[120:123]
	v_mfma_f32_16x16x32_bf16 v[112:115], v[178:181], v[208:211], v[112:115]
	v_mfma_f32_16x16x32_bf16 v[104:107], v[170:173], v[216:219], v[104:107]
	v_mfma_f32_16x16x32_bf16 v[96:99], v[178:181], v[216:219], v[96:99]
	v_mfma_f32_16x16x32_bf16 v[88:91], v[170:173], v[224:227], v[88:91]
	v_mfma_f32_16x16x32_bf16 v[80:83], v[178:181], v[224:227], v[80:83]
	v_mfma_f32_16x16x32_bf16 v[72:75], v[170:173], v[232:235], v[72:75]
	v_mfma_f32_16x16x32_bf16 v[64:67], v[178:181], v[232:235], v[64:67]
	v_mfma_f32_16x16x32_bf16 v[120:123], v[174:177], v[212:215], v[120:123]
	v_mfma_f32_16x16x32_bf16 v[112:115], v[204:207], v[212:215], v[112:115]
	v_mfma_f32_16x16x32_bf16 v[104:107], v[174:177], v[220:223], v[104:107]
	v_mfma_f32_16x16x32_bf16 v[96:99], v[204:207], v[220:223], v[96:99]
	v_mfma_f32_16x16x32_bf16 v[88:91], v[174:177], v[228:231], v[88:91]
	v_mfma_f32_16x16x32_bf16 v[80:83], v[204:207], v[228:231], v[80:83]
	v_mfma_f32_16x16x32_bf16 v[72:75], v[174:177], v[236:239], v[72:75]
	v_mfma_f32_16x16x32_bf16 v[64:67], v[204:207], v[236:239], v[64:67]
	s_setprio 0
	s_barrier
	s_add_i32 s54, s59, s36
	v_lshl_add_u64 v[138:139], v[138:139], 0, s[48:49]
	s_mov_b32 m0, s54
	ds_read_b128 v[208:211], v143 offset:49152
	ds_read_b128 v[212:215], v143 offset:50176
	ds_read_b128 v[216:219], v143 offset:51200
	ds_read_b128 v[220:223], v143 offset:52224
	ds_read_b128 v[224:227], v143 offset:53248
	ds_read_b128 v[228:231], v143 offset:54272
	ds_read_b128 v[232:235], v143 offset:55296
	ds_read_b128 v[236:239], v143 offset:56320
	global_load_lds_dwordx4 v[138:139], off
	s_add_i32 m0, s54, 0x2000
	s_add_u32 s42, s42, 0x40080
	v_lshl_add_u64 v[138:139], v[240:241], 0, s[48:49]
	s_addc_u32 s43, s43, 0
	s_add_i32 s54, s60, s36
	global_load_lds_dwordx4 v[138:139], off
	v_lshl_add_u64 v[138:139], s[42:43], 0, v[144:145]
	s_mov_b32 m0, s54
	s_nop 0
	global_load_lds_dwordx4 v[138:139], off
	v_lshl_add_u64 v[138:139], s[42:43], 0, v[128:129]
	s_add_i32 m0, s54, 0x2000
	s_nop 0
	global_load_lds_dwordx4 v[138:139], off
	v_lshl_add_u64 v[138:139], v[242:243], 0, s[48:49]
	s_mov_b32 m0, s45
	s_nop 0
	global_load_lds_dwordx4 v[138:139], off
	v_lshl_add_u64 v[138:139], v[244:245], 0, s[48:49]
	s_mov_b32 m0, s46
	s_nop 0
	global_load_lds_dwordx4 v[138:139], off
	s_waitcnt vmcnt(8)
	s_waitcnt lgkmcnt(0)
	s_barrier
	s_setprio 1
	s_waitcnt lgkmcnt(0)
	v_mfma_f32_16x16x32_bf16 v[60:63], v[154:157], v[208:211], v[60:63]
	v_mfma_f32_16x16x32_bf16 v[52:55], v[162:165], v[208:211], v[52:55]
	v_mfma_f32_16x16x32_bf16 v[44:47], v[154:157], v[216:219], v[44:47]
	v_mfma_f32_16x16x32_bf16 v[36:39], v[162:165], v[216:219], v[36:39]
	v_mfma_f32_16x16x32_bf16 v[28:31], v[154:157], v[224:227], v[28:31]
	v_mfma_f32_16x16x32_bf16 v[20:23], v[162:165], v[224:227], v[20:23]
	v_mfma_f32_16x16x32_bf16 v[12:15], v[154:157], v[232:235], v[12:15]
	v_mfma_f32_16x16x32_bf16 v[4:7], v[162:165], v[232:235], v[4:7]
	v_mfma_f32_16x16x32_bf16 v[60:63], v[158:161], v[212:215], v[60:63]
	v_mfma_f32_16x16x32_bf16 v[52:55], v[166:169], v[212:215], v[52:55]
	v_mfma_f32_16x16x32_bf16 v[44:47], v[158:161], v[220:223], v[44:47]
	v_mfma_f32_16x16x32_bf16 v[36:39], v[166:169], v[220:223], v[36:39]
	v_mfma_f32_16x16x32_bf16 v[28:31], v[158:161], v[228:231], v[28:31]
	v_mfma_f32_16x16x32_bf16 v[20:23], v[166:169], v[228:231], v[20:23]
	v_mfma_f32_16x16x32_bf16 v[12:15], v[158:161], v[236:239], v[12:15]
	v_mfma_f32_16x16x32_bf16 v[4:7], v[166:169], v[236:239], v[4:7]
	s_setprio 0
	s_setprio 1
	v_mfma_f32_16x16x32_bf16 v[56:59], v[170:173], v[208:211], v[56:59]
	v_mfma_f32_16x16x32_bf16 v[48:51], v[178:181], v[208:211], v[48:51]
	v_mfma_f32_16x16x32_bf16 v[40:43], v[170:173], v[216:219], v[40:43]
	v_mfma_f32_16x16x32_bf16 v[32:35], v[178:181], v[216:219], v[32:35]
	v_mfma_f32_16x16x32_bf16 v[24:27], v[170:173], v[224:227], v[24:27]
	v_mfma_f32_16x16x32_bf16 v[16:19], v[178:181], v[224:227], v[16:19]
	v_mfma_f32_16x16x32_bf16 v[8:11], v[170:173], v[232:235], v[8:11]
	v_mfma_f32_16x16x32_bf16 v[0:3], v[178:181], v[232:235], v[0:3]
	v_mfma_f32_16x16x32_bf16 v[56:59], v[174:177], v[212:215], v[56:59]
	v_mfma_f32_16x16x32_bf16 v[48:51], v[204:207], v[212:215], v[48:51]
	v_mfma_f32_16x16x32_bf16 v[40:43], v[174:177], v[220:223], v[40:43]
	v_mfma_f32_16x16x32_bf16 v[32:35], v[204:207], v[220:223], v[32:35]
	v_mfma_f32_16x16x32_bf16 v[24:27], v[174:177], v[228:231], v[24:27]
	v_mfma_f32_16x16x32_bf16 v[16:19], v[204:207], v[228:231], v[16:19]
	v_mfma_f32_16x16x32_bf16 v[8:11], v[174:177], v[236:239], v[8:11]
	v_mfma_f32_16x16x32_bf16 v[0:3], v[204:207], v[236:239], v[0:3]
	s_setprio 0
	s_barrier
	s_add_i32 s58, s58, 2
	s_add_u32 s56, s56, 0x100
	s_addc_u32 s57, s57, 0
	s_add_u32 s51, s51, 0x100
	s_addc_u32 s53, s53, 0
	s_cmp_gt_u32 s58, 13
	s_cbranch_scc0 .LBB0_345
	s_branch .Lpfi_after
.Lpfi_tail:
	s_add_u32 s42, s56, 0xfffc0080
	s_addc_u32 s43, s57, -1
	s_add_i32 s59, 0, 0x10000
	s_cmp_eq_u32 s58, 12
	s_cselect_b32 s55, s17, s43
	s_cselect_b32 s54, s19, s42
	v_add_u32_e32 v138, s59, v141
	s_cselect_b32 s43, s15, s53
	s_cselect_b32 s42, s50, s51
	s_add_i32 s62, 0, 0x14000
	ds_read_b128 v[154:157], v138
	ds_read_b128 v[158:161], v138 offset:1024
	ds_read_b128 v[162:165], v138 offset:2048
	ds_read_b128 v[166:169], v138 offset:3072
	v_add_u32_e32 v138, s62, v141
	ds_read_b128 v[170:173], v138
	ds_read_b128 v[174:177], v138 offset:1024
	ds_read_b128 v[178:181], v138 offset:2048
	ds_read_b128 v[204:207], v138 offset:3072
	v_lshl_add_u64 v[138:139], s[56:57], 0, v[134:135]
	s_add_i32 m0, s38, 0xc000
	ds_read_b128 v[208:211], v143
	ds_read_b128 v[212:215], v143 offset:1024
	ds_read_b128 v[216:219], v143 offset:2048
	ds_read_b128 v[220:223], v143 offset:3072
	ds_read_b128 v[224:227], v143 offset:4096
	ds_read_b128 v[228:231], v143 offset:5120
	ds_read_b128 v[232:235], v143 offset:6144
	ds_read_b128 v[236:239], v143 offset:7168
	global_load_lds_dwordx4 v[138:139], off
	v_lshl_add_u64 v[138:139], s[56:57], 0, v[136:137]
	s_add_i32 m0, s38, 0xe000
	s_nop 0
	global_load_lds_dwordx4 v[138:139], off
	s_waitcnt vmcnt(8)
	s_waitcnt lgkmcnt(0)
	s_barrier
	s_setprio 1
	s_waitcnt lgkmcnt(0)
	v_mfma_f32_16x16x32_bf16 v[124:127], v[154:157], v[208:211], v[124:127]
	v_mfma_f32_16x16x32_bf16 v[116:119], v[162:165], v[208:211], v[116:119]
	v_mfma_f32_16x16x32_bf16 v[108:111], v[154:157], v[216:219], v[108:111]
	v_mfma_f32_16x16x32_bf16 v[100:103], v[162:165], v[216:219], v[100:103]
	v_mfma_f32_16x16x32_bf16 v[92:95], v[154:157], v[224:227], v[92:95]
	v_mfma_f32_16x16x32_bf16 v[84:87], v[162:165], v[224:227], v[84:87]
	v_mfma_f32_16x16x32_bf16 v[76:79], v[154:157], v[232:235], v[76:79]
	v_mfma_f32_16x16x32_bf16 v[68:71], v[162:165], v[232:235], v[68:71]
	v_mfma_f32_16x16x32_bf16 v[124:127], v[158:161], v[212:215], v[124:127]
	v_mfma_f32_16x16x32_bf16 v[116:119], v[166:169], v[212:215], v[116:119]
	v_mfma_f32_16x16x32_bf16 v[108:111], v[158:161], v[220:223], v[108:111]
	v_mfma_f32_16x16x32_bf16 v[100:103], v[166:169], v[220:223], v[100:103]
	v_mfma_f32_16x16x32_bf16 v[92:95], v[158:161], v[228:231], v[92:95]
	v_mfma_f32_16x16x32_bf16 v[84:87], v[166:169], v[228:231], v[84:87]
	v_mfma_f32_16x16x32_bf16 v[76:79], v[158:161], v[236:239], v[76:79]
	v_mfma_f32_16x16x32_bf16 v[68:71], v[166:169], v[236:239], v[68:71]
	s_setprio 0
	s_setprio 1
	v_mfma_f32_16x16x32_bf16 v[120:123], v[170:173], v[208:211], v[120:123]
	v_mfma_f32_16x16x32_bf16 v[112:115], v[178:181], v[208:211], v[112:115]
	v_mfma_f32_16x16x32_bf16 v[104:107], v[170:173], v[216:219], v[104:107]
	v_mfma_f32_16x16x32_bf16 v[96:99], v[178:181], v[216:219], v[96:99]
	v_mfma_f32_16x16x32_bf16 v[88:91], v[170:173], v[224:227], v[88:91]
	v_mfma_f32_16x16x32_bf16 v[80:83], v[178:181], v[224:227], v[80:83]
	v_mfma_f32_16x16x32_bf16 v[72:75], v[170:173], v[232:235], v[72:75]
	v_mfma_f32_16x16x32_bf16 v[64:67], v[178:181], v[232:235], v[64:67]
	v_mfma_f32_16x16x32_bf16 v[120:123], v[174:177], v[212:215], v[120:123]
	v_mfma_f32_16x16x32_bf16 v[112:115], v[204:207], v[212:215], v[112:115]
	v_mfma_f32_16x16x32_bf16 v[104:107], v[174:177], v[220:223], v[104:107]
	v_mfma_f32_16x16x32_bf16 v[96:99], v[204:207], v[220:223], v[96:99]
	v_mfma_f32_16x16x32_bf16 v[88:91], v[174:177], v[228:231], v[88:91]
	v_mfma_f32_16x16x32_bf16 v[80:83], v[204:207], v[228:231], v[80:83]
	v_mfma_f32_16x16x32_bf16 v[72:75], v[174:177], v[236:239], v[72:75]
	v_mfma_f32_16x16x32_bf16 v[64:67], v[204:207], v[236:239], v[64:67]
	s_setprio 0
	s_barrier
	s_add_i32 s59, s59, s36
	v_lshl_add_u64 v[138:139], s[42:43], 0, v[144:145]
	s_mov_b32 m0, s59
	ds_read_b128 v[208:211], v143 offset:16384
	ds_read_b128 v[212:215], v143 offset:17408
	ds_read_b128 v[216:219], v143 offset:18432
	ds_read_b128 v[220:223], v143 offset:19456
	ds_read_b128 v[224:227], v143 offset:20480
	ds_read_b128 v[228:231], v143 offset:21504
	ds_read_b128 v[232:235], v143 offset:22528
	ds_read_b128 v[236:239], v143 offset:23552
	s_add_i32 m0, s59, 0x2000
	s_add_u32 s60, s42, 0x40000
	v_lshl_add_u64 v[240:241], s[42:43], 0, v[128:129]
	s_addc_u32 s61, s43, 0
	s_add_i32 s59, s62, s36
	v_lshl_add_u64 v[242:243], s[60:61], 0, v[144:145]
	s_mov_b32 m0, s59
	v_lshl_add_u64 v[244:245], s[54:55], 0, v[130:131]
	v_lshl_add_u64 v[242:243], s[60:61], 0, v[128:129]
	s_add_i32 m0, s59, 0x2000
	s_nop 0
	v_lshl_add_u64 v[242:243], s[54:55], 0, v[132:133]
	s_mov_b32 m0, s38
	s_nop 0
	s_mov_b32 m0, s40
	s_nop 0
	s_waitcnt vmcnt(2)
	s_waitcnt lgkmcnt(0)
	s_barrier
	s_setprio 1
	s_waitcnt lgkmcnt(0)
	v_mfma_f32_16x16x32_bf16 v[60:63], v[154:157], v[208:211], v[60:63]
	v_mfma_f32_16x16x32_bf16 v[52:55], v[162:165], v[208:211], v[52:55]
	v_mfma_f32_16x16x32_bf16 v[44:47], v[154:157], v[216:219], v[44:47]
	v_mfma_f32_16x16x32_bf16 v[36:39], v[162:165], v[216:219], v[36:39]
	v_mfma_f32_16x16x32_bf16 v[28:31], v[154:157], v[224:227], v[28:31]
	v_mfma_f32_16x16x32_bf16 v[20:23], v[162:165], v[224:227], v[20:23]
	v_mfma_f32_16x16x32_bf16 v[12:15], v[154:157], v[232:235], v[12:15]
	v_mfma_f32_16x16x32_bf16 v[4:7], v[162:165], v[232:235], v[4:7]
	v_mfma_f32_16x16x32_bf16 v[60:63], v[158:161], v[212:215], v[60:63]
	v_mfma_f32_16x16x32_bf16 v[52:55], v[166:169], v[212:215], v[52:55]
	v_mfma_f32_16x16x32_bf16 v[44:47], v[158:161], v[220:223], v[44:47]
	v_mfma_f32_16x16x32_bf16 v[36:39], v[166:169], v[220:223], v[36:39]
	v_mfma_f32_16x16x32_bf16 v[28:31], v[158:161], v[228:231], v[28:31]
	v_mfma_f32_16x16x32_bf16 v[20:23], v[166:169], v[228:231], v[20:23]
	v_mfma_f32_16x16x32_bf16 v[12:15], v[158:161], v[236:239], v[12:15]
	v_mfma_f32_16x16x32_bf16 v[4:7], v[166:169], v[236:239], v[4:7]
	s_setprio 0
	s_setprio 1
	v_mfma_f32_16x16x32_bf16 v[56:59], v[170:173], v[208:211], v[56:59]
	v_mfma_f32_16x16x32_bf16 v[48:51], v[178:181], v[208:211], v[48:51]
	v_mfma_f32_16x16x32_bf16 v[40:43], v[170:173], v[216:219], v[40:43]
	v_mfma_f32_16x16x32_bf16 v[32:35], v[178:181], v[216:219], v[32:35]
	v_mfma_f32_16x16x32_bf16 v[24:27], v[170:173], v[224:227], v[24:27]
	v_mfma_f32_16x16x32_bf16 v[16:19], v[178:181], v[224:227], v[16:19]
	v_mfma_f32_16x16x32_bf16 v[8:11], v[170:173], v[232:235], v[8:11]
	v_mfma_f32_16x16x32_bf16 v[0:3], v[178:181], v[232:235], v[0:3]
	v_mfma_f32_16x16x32_bf16 v[56:59], v[174:177], v[212:215], v[56:59]
	v_mfma_f32_16x16x32_bf16 v[48:51], v[204:207], v[212:215], v[48:51]
	v_mfma_f32_16x16x32_bf16 v[40:43], v[174:177], v[220:223], v[40:43]
	v_mfma_f32_16x16x32_bf16 v[32:35], v[204:207], v[220:223], v[32:35]
	v_mfma_f32_16x16x32_bf16 v[24:27], v[174:177], v[228:231], v[24:27]
	v_mfma_f32_16x16x32_bf16 v[16:19], v[204:207], v[228:231], v[16:19]
	v_mfma_f32_16x16x32_bf16 v[8:11], v[174:177], v[236:239], v[8:11]
	v_mfma_f32_16x16x32_bf16 v[0:3], v[204:207], v[236:239], v[0:3]
	s_setprio 0
	s_barrier
	s_add_i32 s59, 0, 0x18000
	s_add_i32 s60, 0, 0x1c000
	v_add_u32_e32 v166, s59, v141
	v_add_u32_e32 v190, s60, v141
	ds_read_b128 v[154:157], v166
	ds_read_b128 v[158:161], v166 offset:1024
	ds_read_b128 v[162:165], v166 offset:2048
	ds_read_b128 v[166:169], v166 offset:3072
	ds_read_b128 v[170:173], v190
	ds_read_b128 v[174:177], v190 offset:1024
	ds_read_b128 v[178:181], v190 offset:2048
	ds_read_b128 v[204:207], v190 offset:3072
	s_add_u32 s54, s54, 0x40000
	s_addc_u32 s55, s55, 0
	s_mov_b32 m0, s41
	v_lshl_add_u64 v[246:247], s[54:55], 0, v[132:133]
	ds_read_b128 v[208:211], v143 offset:32768
	ds_read_b128 v[212:215], v143 offset:33792
	ds_read_b128 v[216:219], v143 offset:34816
	ds_read_b128 v[220:223], v143 offset:35840
	ds_read_b128 v[224:227], v143 offset:36864
	ds_read_b128 v[228:231], v143 offset:37888
	ds_read_b128 v[232:235], v143 offset:38912
	ds_read_b128 v[236:239], v143 offset:39936
	v_lshl_add_u64 v[246:247], s[54:55], 0, v[130:131]
	s_mov_b32 m0, s44
	s_nop 0
	s_waitcnt vmcnt(0)
	s_waitcnt lgkmcnt(0)
	s_barrier
	s_setprio 1
	s_waitcnt lgkmcnt(0)
	v_mfma_f32_16x16x32_bf16 v[124:127], v[154:157], v[208:211], v[124:127]
	v_mfma_f32_16x16x32_bf16 v[116:119], v[162:165], v[208:211], v[116:119]
	v_mfma_f32_16x16x32_bf16 v[108:111], v[154:157], v[216:219], v[108:111]
	v_mfma_f32_16x16x32_bf16 v[100:103], v[162:165], v[216:219], v[100:103]
	v_mfma_f32_16x16x32_bf16 v[92:95], v[154:157], v[224:227], v[92:95]
	v_mfma_f32_16x16x32_bf16 v[84:87], v[162:165], v[224:227], v[84:87]
	v_mfma_f32_16x16x32_bf16 v[76:79], v[154:157], v[232:235], v[76:79]
	v_mfma_f32_16x16x32_bf16 v[68:71], v[162:165], v[232:235], v[68:71]
	v_mfma_f32_16x16x32_bf16 v[124:127], v[158:161], v[212:215], v[124:127]
	v_mfma_f32_16x16x32_bf16 v[116:119], v[166:169], v[212:215], v[116:119]
	v_mfma_f32_16x16x32_bf16 v[108:111], v[158:161], v[220:223], v[108:111]
	v_mfma_f32_16x16x32_bf16 v[100:103], v[166:169], v[220:223], v[100:103]
	v_mfma_f32_16x16x32_bf16 v[92:95], v[158:161], v[228:231], v[92:95]
	v_mfma_f32_16x16x32_bf16 v[84:87], v[166:169], v[228:231], v[84:87]
	v_mfma_f32_16x16x32_bf16 v[76:79], v[158:161], v[236:239], v[76:79]
	v_mfma_f32_16x16x32_bf16 v[68:71], v[166:169], v[236:239], v[68:71]
	s_setprio 0
	s_setprio 1
	v_mfma_f32_16x16x32_bf16 v[120:123], v[170:173], v[208:211], v[120:123]
	v_mfma_f32_16x16x32_bf16 v[112:115], v[178:181], v[208:211], v[112:115]
	v_mfma_f32_16x16x32_bf16 v[104:107], v[170:173], v[216:219], v[104:107]
	v_mfma_f32_16x16x32_bf16 v[96:99], v[178:181], v[216:219], v[96:99]
	v_mfma_f32_16x16x32_bf16 v[88:91], v[170:173], v[224:227], v[88:91]
	v_mfma_f32_16x16x32_bf16 v[80:83], v[178:181], v[224:227], v[80:83]
	v_mfma_f32_16x16x32_bf16 v[72:75], v[170:173], v[232:235], v[72:75]
	v_mfma_f32_16x16x32_bf16 v[64:67], v[178:181], v[232:235], v[64:67]
	v_mfma_f32_16x16x32_bf16 v[120:123], v[174:177], v[212:215], v[120:123]
	v_mfma_f32_16x16x32_bf16 v[112:115], v[204:207], v[212:215], v[112:115]
	v_mfma_f32_16x16x32_bf16 v[104:107], v[174:177], v[220:223], v[104:107]
	v_mfma_f32_16x16x32_bf16 v[96:99], v[204:207], v[220:223], v[96:99]
	v_mfma_f32_16x16x32_bf16 v[88:91], v[174:177], v[228:231], v[88:91]
	v_mfma_f32_16x16x32_bf16 v[80:83], v[204:207], v[228:231], v[80:83]
	v_mfma_f32_16x16x32_bf16 v[72:75], v[174:177], v[236:239], v[72:75]
	v_mfma_f32_16x16x32_bf16 v[64:67], v[204:207], v[236:239], v[64:67]
	s_setprio 0
	s_barrier
	s_add_i32 s54, s59, s36
	v_lshl_add_u64 v[138:139], v[138:139], 0, s[48:49]
	s_mov_b32 m0, s54
	ds_read_b128 v[208:211], v143 offset:49152
	ds_read_b128 v[212:215], v143 offset:50176
	ds_read_b128 v[216:219], v143 offset:51200
	ds_read_b128 v[220:223], v143 offset:52224
	ds_read_b128 v[224:227], v143 offset:53248
	ds_read_b128 v[228:231], v143 offset:54272
	ds_read_b128 v[232:235], v143 offset:55296
	ds_read_b128 v[236:239], v143 offset:56320
	s_add_i32 m0, s54, 0x2000
	s_add_u32 s42, s42, 0x40080
	v_lshl_add_u64 v[138:139], v[240:241], 0, s[48:49]
	s_addc_u32 s43, s43, 0
	s_add_i32 s54, s60, s36
	v_lshl_add_u64 v[138:139], s[42:43], 0, v[144:145]
	s_mov_b32 m0, s54
	s_nop 0
	v_lshl_add_u64 v[138:139], s[42:43], 0, v[128:129]
	s_add_i32 m0, s54, 0x2000
	s_nop 0
	v_lshl_add_u64 v[138:139], v[242:243], 0, s[48:49]
	s_mov_b32 m0, s45
	s_nop 0
	v_lshl_add_u64 v[138:139], v[244:245], 0, s[48:49]
	s_mov_b32 m0, s46
	s_nop 0
	s_waitcnt vmcnt(0)
	s_waitcnt lgkmcnt(0)
	s_barrier
	s_setprio 1
	s_waitcnt lgkmcnt(0)
	v_mfma_f32_16x16x32_bf16 v[60:63], v[154:157], v[208:211], v[60:63]
	v_mfma_f32_16x16x32_bf16 v[52:55], v[162:165], v[208:211], v[52:55]
	v_mfma_f32_16x16x32_bf16 v[44:47], v[154:157], v[216:219], v[44:47]
	v_mfma_f32_16x16x32_bf16 v[36:39], v[162:165], v[216:219], v[36:39]
	v_mfma_f32_16x16x32_bf16 v[28:31], v[154:157], v[224:227], v[28:31]
	v_mfma_f32_16x16x32_bf16 v[20:23], v[162:165], v[224:227], v[20:23]
	v_mfma_f32_16x16x32_bf16 v[12:15], v[154:157], v[232:235], v[12:15]
	v_mfma_f32_16x16x32_bf16 v[4:7], v[162:165], v[232:235], v[4:7]
	v_mfma_f32_16x16x32_bf16 v[60:63], v[158:161], v[212:215], v[60:63]
	v_mfma_f32_16x16x32_bf16 v[52:55], v[166:169], v[212:215], v[52:55]
	v_mfma_f32_16x16x32_bf16 v[44:47], v[158:161], v[220:223], v[44:47]
	v_mfma_f32_16x16x32_bf16 v[36:39], v[166:169], v[220:223], v[36:39]
	v_mfma_f32_16x16x32_bf16 v[28:31], v[158:161], v[228:231], v[28:31]
	v_mfma_f32_16x16x32_bf16 v[20:23], v[166:169], v[228:231], v[20:23]
	v_mfma_f32_16x16x32_bf16 v[12:15], v[158:161], v[236:239], v[12:15]
	v_mfma_f32_16x16x32_bf16 v[4:7], v[166:169], v[236:239], v[4:7]
	s_setprio 0
	s_setprio 1
	v_mfma_f32_16x16x32_bf16 v[56:59], v[170:173], v[208:211], v[56:59]
	v_mfma_f32_16x16x32_bf16 v[48:51], v[178:181], v[208:211], v[48:51]
	v_mfma_f32_16x16x32_bf16 v[40:43], v[170:173], v[216:219], v[40:43]
	v_mfma_f32_16x16x32_bf16 v[32:35], v[178:181], v[216:219], v[32:35]
	v_mfma_f32_16x16x32_bf16 v[24:27], v[170:173], v[224:227], v[24:27]
	v_mfma_f32_16x16x32_bf16 v[16:19], v[178:181], v[224:227], v[16:19]
	v_mfma_f32_16x16x32_bf16 v[8:11], v[170:173], v[232:235], v[8:11]
	v_mfma_f32_16x16x32_bf16 v[0:3], v[178:181], v[232:235], v[0:3]
	v_mfma_f32_16x16x32_bf16 v[56:59], v[174:177], v[212:215], v[56:59]
	v_mfma_f32_16x16x32_bf16 v[48:51], v[204:207], v[212:215], v[48:51]
	v_mfma_f32_16x16x32_bf16 v[40:43], v[174:177], v[220:223], v[40:43]
	v_mfma_f32_16x16x32_bf16 v[32:35], v[204:207], v[220:223], v[32:35]
	v_mfma_f32_16x16x32_bf16 v[24:27], v[174:177], v[228:231], v[24:27]
	v_mfma_f32_16x16x32_bf16 v[16:19], v[204:207], v[228:231], v[16:19]
	v_mfma_f32_16x16x32_bf16 v[8:11], v[174:177], v[236:239], v[8:11]
	v_mfma_f32_16x16x32_bf16 v[0:3], v[204:207], v[236:239], v[0:3]
	s_setprio 0
	s_barrier
	s_add_i32 s58, s58, 2
	s_add_u32 s56, s56, 0x100
	s_addc_u32 s57, s57, 0
	s_add_u32 s51, s51, 0x100
	s_addc_u32 s53, s53, 0
	s_cmp_gt_u32 s58, 13
.Lpfi_after:
	s_and_b64 vcc, exec, s[6:7]
	s_cbranch_vccz .LBB0_348
	s_barrier

.LBB0_454:
	s_mov_b32 s101, s4
	s_nop 0
	v_cndmask_b32_e64 v0, 0, 1, s[4:5]
	v_cmp_ne_u32_e64 s[6:7], 1, v0
	s_andn2_b64 vcc, exec, s[4:5]
	s_mul_hi_i32 s17, s51, 0xb00
	s_mul_i32 s22, s51, 0xb00
	s_mov_b64 s[4:5], s[18:19]
	s_cbranch_vccnz .LBB0_456
	s_mul_i32 s5, s53, 0x160000
	s_mul_hi_i32 s4, s53, 0x160000
	s_add_u32 s5, s2, s5
	s_addc_u32 s14, s30, s4
	s_add_u32 s4, s5, s22
	s_addc_u32 s5, s14, s17

.LBB0_459:
	s_cmp_lg_u32 s57, 18
	s_cbranch_scc1 .Lpfo_body
	s_cmp_eq_u32 s101, 0
	s_cbranch_scc1 .Lpfo_tail
.Lpfo_body:
	s_add_u32 s20, s18, 0x100
	s_addc_u32 s21, s19, 0
	s_add_i32 s58, 0, 0x10000
	s_cmp_eq_u32 s57, 18
	s_cselect_b32 s25, s5, s21
	s_cselect_b32 s24, s4, s20
	v_add_u32_e32 v140, s58, v143
	s_cselect_b32 s23, s15, s56
	s_cselect_b32 s22, s14, s17
	s_add_i32 s59, 0, 0x14000
	ds_read_b128 v[156:159], v140
	ds_read_b128 v[160:163], v140 offset:1024
	ds_read_b128 v[164:167], v140 offset:2048
	ds_read_b128 v[168:171], v140 offset:3072
	v_add_u32_e32 v140, s59, v143
	ds_read_b128 v[172:175], v140
	ds_read_b128 v[176:179], v140 offset:1024
	ds_read_b128 v[204:207], v140 offset:2048
	ds_read_b128 v[208:211], v140 offset:3072
	v_lshl_add_u64 v[140:141], s[18:19], 0, v[136:137]
	s_add_i32 m0, s37, 0xc000
	ds_read_b128 v[212:215], v154
	ds_read_b128 v[216:219], v154 offset:1024
	ds_read_b128 v[220:223], v154 offset:2048
	ds_read_b128 v[224:227], v154 offset:3072
	ds_read_b128 v[228:231], v154 offset:4096
	ds_read_b128 v[232:235], v154 offset:5120
	ds_read_b128 v[236:239], v154 offset:6144
	ds_read_b128 v[240:243], v154 offset:7168
	global_load_lds_dwordx4 v[140:141], off
	v_lshl_add_u64 v[140:141], s[18:19], 0, v[138:139]
	s_add_i32 m0, s37, 0xe000
	s_nop 0
	global_load_lds_dwordx4 v[140:141], off
	s_waitcnt vmcnt(8)
	s_waitcnt lgkmcnt(0)
	s_barrier
	s_setprio 1
	s_waitcnt lgkmcnt(0)
	v_mfma_f32_16x16x32_bf16 v[124:127], v[156:159], v[212:215], v[124:127]
	v_mfma_f32_16x16x32_bf16 v[120:123], v[164:167], v[212:215], v[120:123]
	v_mfma_f32_16x16x32_bf16 v[116:119], v[156:159], v[220:223], v[116:119]
	v_mfma_f32_16x16x32_bf16 v[108:111], v[164:167], v[220:223], v[108:111]
	v_mfma_f32_16x16x32_bf16 v[100:103], v[156:159], v[228:231], v[100:103]
	v_mfma_f32_16x16x32_bf16 v[92:95], v[164:167], v[228:231], v[92:95]
	v_mfma_f32_16x16x32_bf16 v[84:87], v[156:159], v[236:239], v[84:87]
	v_mfma_f32_16x16x32_bf16 v[76:79], v[164:167], v[236:239], v[76:79]
	v_mfma_f32_16x16x32_bf16 v[124:127], v[160:163], v[216:219], v[124:127]
	v_mfma_f32_16x16x32_bf16 v[120:123], v[168:171], v[216:219], v[120:123]
	v_mfma_f32_16x16x32_bf16 v[116:119], v[160:163], v[224:227], v[116:119]
	v_mfma_f32_16x16x32_bf16 v[108:111], v[168:171], v[224:227], v[108:111]
	v_mfma_f32_16x16x32_bf16 v[100:103], v[160:163], v[232:235], v[100:103]
	v_mfma_f32_16x16x32_bf16 v[92:95], v[168:171], v[232:235], v[92:95]
	v_mfma_f32_16x16x32_bf16 v[84:87], v[160:163], v[240:243], v[84:87]
	v_mfma_f32_16x16x32_bf16 v[76:79], v[168:171], v[240:243], v[76:79]
	s_setprio 0
	s_setprio 1
	v_mfma_f32_16x16x32_bf16 v[112:115], v[172:175], v[212:215], v[112:115]
	v_mfma_f32_16x16x32_bf16 v[104:107], v[204:207], v[212:215], v[104:107]
	v_mfma_f32_16x16x32_bf16 v[96:99], v[172:175], v[220:223], v[96:99]
	v_mfma_f32_16x16x32_bf16 v[88:91], v[204:207], v[220:223], v[88:91]
	v_mfma_f32_16x16x32_bf16 v[80:83], v[172:175], v[228:231], v[80:83]
	v_mfma_f32_16x16x32_bf16 v[72:75], v[204:207], v[228:231], v[72:75]
	v_mfma_f32_16x16x32_bf16 v[68:71], v[172:175], v[236:239], v[68:71]
	v_mfma_f32_16x16x32_bf16 v[64:67], v[204:207], v[236:239], v[64:67]
	v_mfma_f32_16x16x32_bf16 v[112:115], v[176:179], v[216:219], v[112:115]
	v_mfma_f32_16x16x32_bf16 v[104:107], v[208:211], v[216:219], v[104:107]
	v_mfma_f32_16x16x32_bf16 v[96:99], v[176:179], v[224:227], v[96:99]
	v_mfma_f32_16x16x32_bf16 v[88:91], v[208:211], v[224:227], v[88:91]
	v_mfma_f32_16x16x32_bf16 v[80:83], v[176:179], v[232:235], v[80:83]
	v_mfma_f32_16x16x32_bf16 v[72:75], v[208:211], v[232:235], v[72:75]
	v_mfma_f32_16x16x32_bf16 v[68:71], v[176:179], v[240:243], v[68:71]
	v_mfma_f32_16x16x32_bf16 v[64:67], v[208:211], v[240:243], v[64:67]
	s_setprio 0
	s_barrier
	s_add_i32 s18, s58, s36
	v_lshl_add_u64 v[140:141], s[22:23], 0, v[130:131]
	s_mov_b32 m0, s18
	ds_read_b128 v[212:215], v154 offset:16384
	ds_read_b128 v[216:219], v154 offset:17408
	ds_read_b128 v[220:223], v154 offset:18432
	ds_read_b128 v[224:227], v154 offset:19456
	ds_read_b128 v[228:231], v154 offset:20480
	ds_read_b128 v[232:235], v154 offset:21504
	ds_read_b128 v[236:239], v154 offset:22528
	ds_read_b128 v[240:243], v154 offset:23552
	global_load_lds_dwordx4 v[140:141], off
	s_add_i32 m0, s18, 0x2000
	s_add_u32 s18, s22, 0xb0000
	v_lshl_add_u64 v[180:181], s[22:23], 0, v[134:135]
	s_addc_u32 s19, s23, 0
	s_add_i32 s58, s59, s36
	global_load_lds_dwordx4 v[180:181], off
	v_lshl_add_u64 v[244:245], s[18:19], 0, v[130:131]
	s_mov_b32 m0, s58
	v_lshl_add_u64 v[246:247], s[24:25], 0, v[132:133]
	global_load_lds_dwordx4 v[244:245], off
	v_lshl_add_u64 v[244:245], s[18:19], 0, v[134:135]
	s_add_i32 m0, s58, 0x2000
	s_nop 0
	global_load_lds_dwordx4 v[244:245], off
	v_lshl_add_u64 v[244:245], s[24:25], 0, v[128:129]
	s_mov_b32 m0, s37
	s_nop 0
	global_load_lds_dwordx4 v[244:245], off
	s_mov_b32 m0, s40
	s_nop 0
	global_load_lds_dwordx4 v[246:247], off
	s_waitcnt vmcnt(8)
	s_waitcnt lgkmcnt(0)
	s_barrier
	s_setprio 1
	s_waitcnt lgkmcnt(0)
	v_mfma_f32_16x16x32_bf16 v[60:63], v[156:159], v[212:215], v[60:63]
	v_mfma_f32_16x16x32_bf16 v[56:59], v[164:167], v[212:215], v[56:59]
	v_mfma_f32_16x16x32_bf16 v[52:55], v[156:159], v[220:223], v[52:55]
	v_mfma_f32_16x16x32_bf16 v[44:47], v[164:167], v[220:223], v[44:47]
	v_mfma_f32_16x16x32_bf16 v[36:39], v[156:159], v[228:231], v[36:39]
	v_mfma_f32_16x16x32_bf16 v[28:31], v[164:167], v[228:231], v[28:31]
	v_mfma_f32_16x16x32_bf16 v[20:23], v[156:159], v[236:239], v[20:23]
	v_mfma_f32_16x16x32_bf16 v[12:15], v[164:167], v[236:239], v[12:15]
	v_mfma_f32_16x16x32_bf16 v[60:63], v[160:163], v[216:219], v[60:63]
	v_mfma_f32_16x16x32_bf16 v[56:59], v[168:171], v[216:219], v[56:59]
	v_mfma_f32_16x16x32_bf16 v[52:55], v[160:163], v[224:227], v[52:55]
	v_mfma_f32_16x16x32_bf16 v[44:47], v[168:171], v[224:227], v[44:47]
	v_mfma_f32_16x16x32_bf16 v[36:39], v[160:163], v[232:235], v[36:39]
	v_mfma_f32_16x16x32_bf16 v[28:31], v[168:171], v[232:235], v[28:31]
	v_mfma_f32_16x16x32_bf16 v[20:23], v[160:163], v[240:243], v[20:23]
	v_mfma_f32_16x16x32_bf16 v[12:15], v[168:171], v[240:243], v[12:15]
	s_setprio 0
	s_setprio 1
	v_mfma_f32_16x16x32_bf16 v[48:51], v[172:175], v[212:215], v[48:51]
	v_mfma_f32_16x16x32_bf16 v[40:43], v[204:207], v[212:215], v[40:43]
	v_mfma_f32_16x16x32_bf16 v[32:35], v[172:175], v[220:223], v[32:35]
	v_mfma_f32_16x16x32_bf16 v[24:27], v[204:207], v[220:223], v[24:27]
	v_mfma_f32_16x16x32_bf16 v[16:19], v[172:175], v[228:231], v[16:19]
	v_mfma_f32_16x16x32_bf16 v[8:11], v[204:207], v[228:231], v[8:11]
	v_mfma_f32_16x16x32_bf16 v[4:7], v[172:175], v[236:239], v[4:7]
	v_mfma_f32_16x16x32_bf16 v[0:3], v[204:207], v[236:239], v[0:3]
	v_mfma_f32_16x16x32_bf16 v[48:51], v[176:179], v[216:219], v[48:51]
	v_mfma_f32_16x16x32_bf16 v[40:43], v[208:211], v[216:219], v[40:43]
	v_mfma_f32_16x16x32_bf16 v[32:35], v[176:179], v[224:227], v[32:35]
	v_mfma_f32_16x16x32_bf16 v[24:27], v[208:211], v[224:227], v[24:27]
	v_mfma_f32_16x16x32_bf16 v[16:19], v[176:179], v[232:235], v[16:19]
	v_mfma_f32_16x16x32_bf16 v[8:11], v[208:211], v[232:235], v[8:11]
	v_mfma_f32_16x16x32_bf16 v[4:7], v[176:179], v[240:243], v[4:7]
	v_mfma_f32_16x16x32_bf16 v[0:3], v[208:211], v[240:243], v[0:3]
	s_setprio 0
	s_barrier
	s_add_i32 s58, 0, 0x18000
	v_add_u32_e32 v155, s58, v143
	s_add_i32 s59, 0, 0x1c000
	ds_read_b128 v[156:159], v155
	ds_read_b128 v[160:163], v155 offset:1024
	ds_read_b128 v[164:167], v155 offset:2048
	ds_read_b128 v[168:171], v155 offset:3072
	v_add_u32_e32 v155, s59, v143
	ds_read_b128 v[172:175], v155
	ds_read_b128 v[176:179], v155 offset:1024
	ds_read_b128 v[204:207], v155 offset:2048
	ds_read_b128 v[208:211], v155 offset:3072
	s_add_u32 s18, s24, 0xb0000
	s_addc_u32 s19, s25, 0
	s_mov_b32 m0, s41
	v_lshl_add_u64 v[248:249], s[18:19], 0, v[128:129]
	ds_read_b128 v[212:215], v154 offset:32768
	ds_read_b128 v[216:219], v154 offset:33792
	ds_read_b128 v[220:223], v154 offset:34816
	ds_read_b128 v[224:227], v154 offset:35840
	ds_read_b128 v[228:231], v154 offset:36864
	ds_read_b128 v[232:235], v154 offset:37888
	ds_read_b128 v[236:239], v154 offset:38912
	ds_read_b128 v[240:243], v154 offset:39936
	global_load_lds_dwordx4 v[248:249], off
	v_lshl_add_u64 v[248:249], s[18:19], 0, v[132:133]
	s_mov_b32 m0, s42
	s_nop 0
	global_load_lds_dwordx4 v[248:249], off
	s_waitcnt vmcnt(8)
	s_waitcnt lgkmcnt(0)
	s_barrier
	s_setprio 1
	s_waitcnt lgkmcnt(0)
	v_mfma_f32_16x16x32_bf16 v[124:127], v[156:159], v[212:215], v[124:127]
	v_mfma_f32_16x16x32_bf16 v[120:123], v[164:167], v[212:215], v[120:123]
	v_mfma_f32_16x16x32_bf16 v[116:119], v[156:159], v[220:223], v[116:119]
	v_mfma_f32_16x16x32_bf16 v[108:111], v[164:167], v[220:223], v[108:111]
	v_mfma_f32_16x16x32_bf16 v[100:103], v[156:159], v[228:231], v[100:103]
	v_mfma_f32_16x16x32_bf16 v[92:95], v[164:167], v[228:231], v[92:95]
	v_mfma_f32_16x16x32_bf16 v[84:87], v[156:159], v[236:239], v[84:87]
	v_mfma_f32_16x16x32_bf16 v[76:79], v[164:167], v[236:239], v[76:79]
	v_mfma_f32_16x16x32_bf16 v[124:127], v[160:163], v[216:219], v[124:127]
	v_mfma_f32_16x16x32_bf16 v[120:123], v[168:171], v[216:219], v[120:123]
	v_mfma_f32_16x16x32_bf16 v[116:119], v[160:163], v[224:227], v[116:119]
	v_mfma_f32_16x16x32_bf16 v[108:111], v[168:171], v[224:227], v[108:111]
	v_mfma_f32_16x16x32_bf16 v[100:103], v[160:163], v[232:235], v[100:103]
	v_mfma_f32_16x16x32_bf16 v[92:95], v[168:171], v[232:235], v[92:95]
	v_mfma_f32_16x16x32_bf16 v[84:87], v[160:163], v[240:243], v[84:87]
	v_mfma_f32_16x16x32_bf16 v[76:79], v[168:171], v[240:243], v[76:79]
	s_setprio 0
	s_setprio 1
	v_mfma_f32_16x16x32_bf16 v[112:115], v[172:175], v[212:215], v[112:115]
	v_mfma_f32_16x16x32_bf16 v[104:107], v[204:207], v[212:215], v[104:107]
	v_mfma_f32_16x16x32_bf16 v[96:99], v[172:175], v[220:223], v[96:99]
	v_mfma_f32_16x16x32_bf16 v[88:91], v[204:207], v[220:223], v[88:91]
	v_mfma_f32_16x16x32_bf16 v[80:83], v[172:175], v[228:231], v[80:83]
	v_mfma_f32_16x16x32_bf16 v[72:75], v[204:207], v[228:231], v[72:75]
	v_mfma_f32_16x16x32_bf16 v[68:71], v[172:175], v[236:239], v[68:71]
	v_mfma_f32_16x16x32_bf16 v[64:67], v[204:207], v[236:239], v[64:67]
	v_mfma_f32_16x16x32_bf16 v[112:115], v[176:179], v[216:219], v[112:115]
	v_mfma_f32_16x16x32_bf16 v[104:107], v[208:211], v[216:219], v[104:107]
	v_mfma_f32_16x16x32_bf16 v[96:99], v[176:179], v[224:227], v[96:99]
	v_mfma_f32_16x16x32_bf16 v[88:91], v[208:211], v[224:227], v[88:91]
	v_mfma_f32_16x16x32_bf16 v[80:83], v[176:179], v[232:235], v[80:83]
	v_mfma_f32_16x16x32_bf16 v[72:75], v[208:211], v[232:235], v[72:75]
	v_mfma_f32_16x16x32_bf16 v[68:71], v[176:179], v[240:243], v[68:71]
	v_mfma_f32_16x16x32_bf16 v[64:67], v[208:211], v[240:243], v[64:67]
	s_setprio 0
	s_barrier
	s_add_i32 s18, s58, s36
	v_lshl_add_u64 v[140:141], v[140:141], 0, s[48:49]
	s_mov_b32 m0, s18
	ds_read_b128 v[212:215], v154 offset:49152
	ds_read_b128 v[216:219], v154 offset:50176
	ds_read_b128 v[220:223], v154 offset:51200
	ds_read_b128 v[224:227], v154 offset:52224
	ds_read_b128 v[228:231], v154 offset:53248
	ds_read_b128 v[232:235], v154 offset:54272
	ds_read_b128 v[236:239], v154 offset:55296
	ds_read_b128 v[240:243], v154 offset:56320
	global_load_lds_dwordx4 v[140:141], off
	s_add_i32 m0, s18, 0x2000
	s_add_u32 s18, s22, 0xb0080
	v_lshl_add_u64 v[140:141], v[180:181], 0, s[48:49]
	s_addc_u32 s19, s23, 0
	s_add_i32 s22, s59, s36
	global_load_lds_dwordx4 v[140:141], off
	v_lshl_add_u64 v[140:141], s[18:19], 0, v[130:131]
	s_mov_b32 m0, s22
	s_nop 0
	global_load_lds_dwordx4 v[140:141], off
	v_lshl_add_u64 v[140:141], s[18:19], 0, v[134:135]
	s_add_i32 m0, s22, 0x2000
	s_nop 0
	global_load_lds_dwordx4 v[140:141], off
	v_lshl_add_u64 v[140:141], v[244:245], 0, s[48:49]
	s_mov_b32 m0, s43
	s_nop 0
	global_load_lds_dwordx4 v[140:141], off
	v_lshl_add_u64 v[140:141], v[246:247], 0, s[48:49]
	s_mov_b32 m0, s44
	s_nop 0
	global_load_lds_dwordx4 v[140:141], off
	s_waitcnt vmcnt(8)
	s_waitcnt lgkmcnt(0)
	s_barrier
	s_setprio 1
	s_waitcnt lgkmcnt(0)
	v_mfma_f32_16x16x32_bf16 v[60:63], v[156:159], v[212:215], v[60:63]
	v_mfma_f32_16x16x32_bf16 v[56:59], v[164:167], v[212:215], v[56:59]
	v_mfma_f32_16x16x32_bf16 v[52:55], v[156:159], v[220:223], v[52:55]
	v_mfma_f32_16x16x32_bf16 v[44:47], v[164:167], v[220:223], v[44:47]
	v_mfma_f32_16x16x32_bf16 v[36:39], v[156:159], v[228:231], v[36:39]
	v_mfma_f32_16x16x32_bf16 v[28:31], v[164:167], v[228:231], v[28:31]
	v_mfma_f32_16x16x32_bf16 v[20:23], v[156:159], v[236:239], v[20:23]
	v_mfma_f32_16x16x32_bf16 v[12:15], v[164:167], v[236:239], v[12:15]
	v_mfma_f32_16x16x32_bf16 v[60:63], v[160:163], v[216:219], v[60:63]
	v_mfma_f32_16x16x32_bf16 v[56:59], v[168:171], v[216:219], v[56:59]
	v_mfma_f32_16x16x32_bf16 v[52:55], v[160:163], v[224:227], v[52:55]
	v_mfma_f32_16x16x32_bf16 v[44:47], v[168:171], v[224:227], v[44:47]
	v_mfma_f32_16x16x32_bf16 v[36:39], v[160:163], v[232:235], v[36:39]
	v_mfma_f32_16x16x32_bf16 v[28:31], v[168:171], v[232:235], v[28:31]
	v_mfma_f32_16x16x32_bf16 v[20:23], v[160:163], v[240:243], v[20:23]
	v_mfma_f32_16x16x32_bf16 v[12:15], v[168:171], v[240:243], v[12:15]
	s_setprio 0
	s_setprio 1
	v_mfma_f32_16x16x32_bf16 v[48:51], v[172:175], v[212:215], v[48:51]
	v_mfma_f32_16x16x32_bf16 v[40:43], v[204:207], v[212:215], v[40:43]
	v_mfma_f32_16x16x32_bf16 v[32:35], v[172:175], v[220:223], v[32:35]
	v_mfma_f32_16x16x32_bf16 v[24:27], v[204:207], v[220:223], v[24:27]
	v_mfma_f32_16x16x32_bf16 v[16:19], v[172:175], v[228:231], v[16:19]
	v_mfma_f32_16x16x32_bf16 v[8:11], v[204:207], v[228:231], v[8:11]
	v_mfma_f32_16x16x32_bf16 v[4:7], v[172:175], v[236:239], v[4:7]
	v_mfma_f32_16x16x32_bf16 v[0:3], v[204:207], v[236:239], v[0:3]
	v_mfma_f32_16x16x32_bf16 v[48:51], v[176:179], v[216:219], v[48:51]
	v_mfma_f32_16x16x32_bf16 v[40:43], v[208:211], v[216:219], v[40:43]
	v_mfma_f32_16x16x32_bf16 v[32:35], v[176:179], v[224:227], v[32:35]
	v_mfma_f32_16x16x32_bf16 v[24:27], v[208:211], v[224:227], v[24:27]
	v_mfma_f32_16x16x32_bf16 v[16:19], v[176:179], v[232:235], v[16:19]
	v_mfma_f32_16x16x32_bf16 v[8:11], v[208:211], v[232:235], v[8:11]
	v_mfma_f32_16x16x32_bf16 v[4:7], v[176:179], v[240:243], v[4:7]
	v_mfma_f32_16x16x32_bf16 v[0:3], v[208:211], v[240:243], v[0:3]
	s_setprio 0
	s_barrier
	s_add_i32 s57, s57, 2
	s_add_u32 s17, s17, 0x100
	s_addc_u32 s56, s56, 0
	s_cmp_gt_u32 s57, 19
	s_mov_b64 s[18:19], s[20:21]
	s_cbranch_scc0 .LBB0_459
	s_branch .Lpfo_after
.Lpfo_tail:
	s_add_u32 s20, s18, 0x100
	s_addc_u32 s21, s19, 0
	s_add_i32 s58, 0, 0x10000
	s_cmp_eq_u32 s57, 18
	s_cselect_b32 s25, s5, s21
	s_cselect_b32 s24, s4, s20
	v_add_u32_e32 v140, s58, v143
	s_cselect_b32 s23, s15, s56
	s_cselect_b32 s22, s14, s17
	s_add_i32 s59, 0, 0x14000
	ds_read_b128 v[156:159], v140
	ds_read_b128 v[160:163], v140 offset:1024
	ds_read_b128 v[164:167], v140 offset:2048
	ds_read_b128 v[168:171], v140 offset:3072
	v_add_u32_e32 v140, s59, v143
	ds_read_b128 v[172:175], v140
	ds_read_b128 v[176:179], v140 offset:1024
	ds_read_b128 v[204:207], v140 offset:2048
	ds_read_b128 v[208:211], v140 offset:3072
	v_lshl_add_u64 v[140:141], s[18:19], 0, v[136:137]
	s_add_i32 m0, s37, 0xc000
	ds_read_b128 v[212:215], v154
	ds_read_b128 v[216:219], v154 offset:1024
	ds_read_b128 v[220:223], v154 offset:2048
	ds_read_b128 v[224:227], v154 offset:3072
	ds_read_b128 v[228:231], v154 offset:4096
	ds_read_b128 v[232:235], v154 offset:5120
	ds_read_b128 v[236:239], v154 offset:6144
	ds_read_b128 v[240:243], v154 offset:7168
	global_load_lds_dwordx4 v[140:141], off
	v_lshl_add_u64 v[140:141], s[18:19], 0, v[138:139]
	s_add_i32 m0, s37, 0xe000
	s_nop 0
	global_load_lds_dwordx4 v[140:141], off
	s_waitcnt vmcnt(8)
	s_waitcnt lgkmcnt(0)
	s_barrier
	s_setprio 1
	s_waitcnt lgkmcnt(0)
	v_mfma_f32_16x16x32_bf16 v[124:127], v[156:159], v[212:215], v[124:127]
	v_mfma_f32_16x16x32_bf16 v[120:123], v[164:167], v[212:215], v[120:123]
	v_mfma_f32_16x16x32_bf16 v[116:119], v[156:159], v[220:223], v[116:119]
	v_mfma_f32_16x16x32_bf16 v[108:111], v[164:167], v[220:223], v[108:111]
	v_mfma_f32_16x16x32_bf16 v[100:103], v[156:159], v[228:231], v[100:103]
	v_mfma_f32_16x16x32_bf16 v[92:95], v[164:167], v[228:231], v[92:95]
	v_mfma_f32_16x16x32_bf16 v[84:87], v[156:159], v[236:239], v[84:87]
	v_mfma_f32_16x16x32_bf16 v[76:79], v[164:167], v[236:239], v[76:79]
	v_mfma_f32_16x16x32_bf16 v[124:127], v[160:163], v[216:219], v[124:127]
	v_mfma_f32_16x16x32_bf16 v[120:123], v[168:171], v[216:219], v[120:123]
	v_mfma_f32_16x16x32_bf16 v[116:119], v[160:163], v[224:227], v[116:119]
	v_mfma_f32_16x16x32_bf16 v[108:111], v[168:171], v[224:227], v[108:111]
	v_mfma_f32_16x16x32_bf16 v[100:103], v[160:163], v[232:235], v[100:103]
	v_mfma_f32_16x16x32_bf16 v[92:95], v[168:171], v[232:235], v[92:95]
	v_mfma_f32_16x16x32_bf16 v[84:87], v[160:163], v[240:243], v[84:87]
	v_mfma_f32_16x16x32_bf16 v[76:79], v[168:171], v[240:243], v[76:79]
	s_setprio 0
	s_setprio 1
	v_mfma_f32_16x16x32_bf16 v[112:115], v[172:175], v[212:215], v[112:115]
	v_mfma_f32_16x16x32_bf16 v[104:107], v[204:207], v[212:215], v[104:107]
	v_mfma_f32_16x16x32_bf16 v[96:99], v[172:175], v[220:223], v[96:99]
	v_mfma_f32_16x16x32_bf16 v[88:91], v[204:207], v[220:223], v[88:91]
	v_mfma_f32_16x16x32_bf16 v[80:83], v[172:175], v[228:231], v[80:83]
	v_mfma_f32_16x16x32_bf16 v[72:75], v[204:207], v[228:231], v[72:75]
	v_mfma_f32_16x16x32_bf16 v[68:71], v[172:175], v[236:239], v[68:71]
	v_mfma_f32_16x16x32_bf16 v[64:67], v[204:207], v[236:239], v[64:67]
	v_mfma_f32_16x16x32_bf16 v[112:115], v[176:179], v[216:219], v[112:115]
	v_mfma_f32_16x16x32_bf16 v[104:107], v[208:211], v[216:219], v[104:107]
	v_mfma_f32_16x16x32_bf16 v[96:99], v[176:179], v[224:227], v[96:99]
	v_mfma_f32_16x16x32_bf16 v[88:91], v[208:211], v[224:227], v[88:91]
	v_mfma_f32_16x16x32_bf16 v[80:83], v[176:179], v[232:235], v[80:83]
	v_mfma_f32_16x16x32_bf16 v[72:75], v[208:211], v[232:235], v[72:75]
	v_mfma_f32_16x16x32_bf16 v[68:71], v[176:179], v[240:243], v[68:71]
	v_mfma_f32_16x16x32_bf16 v[64:67], v[208:211], v[240:243], v[64:67]
	s_setprio 0
	s_barrier
	s_add_i32 s18, s58, s36
	v_lshl_add_u64 v[140:141], s[22:23], 0, v[130:131]
	s_mov_b32 m0, s18
	ds_read_b128 v[212:215], v154 offset:16384
	ds_read_b128 v[216:219], v154 offset:17408
	ds_read_b128 v[220:223], v154 offset:18432
	ds_read_b128 v[224:227], v154 offset:19456
	ds_read_b128 v[228:231], v154 offset:20480
	ds_read_b128 v[232:235], v154 offset:21504
	ds_read_b128 v[236:239], v154 offset:22528
	ds_read_b128 v[240:243], v154 offset:23552
	s_add_i32 m0, s18, 0x2000
	s_add_u32 s18, s22, 0xb0000
	v_lshl_add_u64 v[180:181], s[22:23], 0, v[134:135]
	s_addc_u32 s19, s23, 0
	s_add_i32 s58, s59, s36
	v_lshl_add_u64 v[244:245], s[18:19], 0, v[130:131]
	s_mov_b32 m0, s58
	v_lshl_add_u64 v[246:247], s[24:25], 0, v[132:133]
	v_lshl_add_u64 v[244:245], s[18:19], 0, v[134:135]
	s_add_i32 m0, s58, 0x2000
	s_nop 0
	v_lshl_add_u64 v[244:245], s[24:25], 0, v[128:129]
	s_mov_b32 m0, s37
	s_nop 0
	s_mov_b32 m0, s40
	s_nop 0
	s_waitcnt vmcnt(2)
	s_waitcnt lgkmcnt(0)
	s_barrier
	s_setprio 1
	s_waitcnt lgkmcnt(0)
	v_mfma_f32_16x16x32_bf16 v[60:63], v[156:159], v[212:215], v[60:63]
	v_mfma_f32_16x16x32_bf16 v[56:59], v[164:167], v[212:215], v[56:59]
	v_mfma_f32_16x16x32_bf16 v[52:55], v[156:159], v[220:223], v[52:55]
	v_mfma_f32_16x16x32_bf16 v[44:47], v[164:167], v[220:223], v[44:47]
	v_mfma_f32_16x16x32_bf16 v[36:39], v[156:159], v[228:231], v[36:39]
	v_mfma_f32_16x16x32_bf16 v[28:31], v[164:167], v[228:231], v[28:31]
	v_mfma_f32_16x16x32_bf16 v[20:23], v[156:159], v[236:239], v[20:23]
	v_mfma_f32_16x16x32_bf16 v[12:15], v[164:167], v[236:239], v[12:15]
	v_mfma_f32_16x16x32_bf16 v[60:63], v[160:163], v[216:219], v[60:63]
	v_mfma_f32_16x16x32_bf16 v[56:59], v[168:171], v[216:219], v[56:59]
	v_mfma_f32_16x16x32_bf16 v[52:55], v[160:163], v[224:227], v[52:55]
	v_mfma_f32_16x16x32_bf16 v[44:47], v[168:171], v[224:227], v[44:47]
	v_mfma_f32_16x16x32_bf16 v[36:39], v[160:163], v[232:235], v[36:39]
	v_mfma_f32_16x16x32_bf16 v[28:31], v[168:171], v[232:235], v[28:31]
	v_mfma_f32_16x16x32_bf16 v[20:23], v[160:163], v[240:243], v[20:23]
	v_mfma_f32_16x16x32_bf16 v[12:15], v[168:171], v[240:243], v[12:15]
	s_setprio 0
	s_setprio 1
	v_mfma_f32_16x16x32_bf16 v[48:51], v[172:175], v[212:215], v[48:51]
	v_mfma_f32_16x16x32_bf16 v[40:43], v[204:207], v[212:215], v[40:43]
	v_mfma_f32_16x16x32_bf16 v[32:35], v[172:175], v[220:223], v[32:35]
	v_mfma_f32_16x16x32_bf16 v[24:27], v[204:207], v[220:223], v[24:27]
	v_mfma_f32_16x16x32_bf16 v[16:19], v[172:175], v[228:231], v[16:19]
	v_mfma_f32_16x16x32_bf16 v[8:11], v[204:207], v[228:231], v[8:11]
	v_mfma_f32_16x16x32_bf16 v[4:7], v[172:175], v[236:239], v[4:7]
	v_mfma_f32_16x16x32_bf16 v[0:3], v[204:207], v[236:239], v[0:3]
	v_mfma_f32_16x16x32_bf16 v[48:51], v[176:179], v[216:219], v[48:51]
	v_mfma_f32_16x16x32_bf16 v[40:43], v[208:211], v[216:219], v[40:43]
	v_mfma_f32_16x16x32_bf16 v[32:35], v[176:179], v[224:227], v[32:35]
	v_mfma_f32_16x16x32_bf16 v[24:27], v[208:211], v[224:227], v[24:27]
	v_mfma_f32_16x16x32_bf16 v[16:19], v[176:179], v[232:235], v[16:19]
	v_mfma_f32_16x16x32_bf16 v[8:11], v[208:211], v[232:235], v[8:11]
	v_mfma_f32_16x16x32_bf16 v[4:7], v[176:179], v[240:243], v[4:7]
	v_mfma_f32_16x16x32_bf16 v[0:3], v[208:211], v[240:243], v[0:3]
	s_setprio 0
	s_barrier
	s_add_i32 s58, 0, 0x18000
	v_add_u32_e32 v155, s58, v143
	s_add_i32 s59, 0, 0x1c000
	ds_read_b128 v[156:159], v155
	ds_read_b128 v[160:163], v155 offset:1024
	ds_read_b128 v[164:167], v155 offset:2048
	ds_read_b128 v[168:171], v155 offset:3072
	v_add_u32_e32 v155, s59, v143
	ds_read_b128 v[172:175], v155
	ds_read_b128 v[176:179], v155 offset:1024
	ds_read_b128 v[204:207], v155 offset:2048
	ds_read_b128 v[208:211], v155 offset:3072
	s_add_u32 s18, s24, 0xb0000
	s_addc_u32 s19, s25, 0
	s_mov_b32 m0, s41
	v_lshl_add_u64 v[248:249], s[18:19], 0, v[128:129]
	ds_read_b128 v[212:215], v154 offset:32768
	ds_read_b128 v[216:219], v154 offset:33792
	ds_read_b128 v[220:223], v154 offset:34816
	ds_read_b128 v[224:227], v154 offset:35840
	ds_read_b128 v[228:231], v154 offset:36864
	ds_read_b128 v[232:235], v154 offset:37888
	ds_read_b128 v[236:239], v154 offset:38912
	ds_read_b128 v[240:243], v154 offset:39936
	v_lshl_add_u64 v[248:249], s[18:19], 0, v[132:133]
	s_mov_b32 m0, s42
	s_nop 0
	s_waitcnt vmcnt(0)
	s_waitcnt lgkmcnt(0)
	s_barrier
	s_setprio 1
	s_waitcnt lgkmcnt(0)
	v_mfma_f32_16x16x32_bf16 v[124:127], v[156:159], v[212:215], v[124:127]
	v_mfma_f32_16x16x32_bf16 v[120:123], v[164:167], v[212:215], v[120:123]
	v_mfma_f32_16x16x32_bf16 v[116:119], v[156:159], v[220:223], v[116:119]
	v_mfma_f32_16x16x32_bf16 v[108:111], v[164:167], v[220:223], v[108:111]
	v_mfma_f32_16x16x32_bf16 v[100:103], v[156:159], v[228:231], v[100:103]
	v_mfma_f32_16x16x32_bf16 v[92:95], v[164:167], v[228:231], v[92:95]
	v_mfma_f32_16x16x32_bf16 v[84:87], v[156:159], v[236:239], v[84:87]
	v_mfma_f32_16x16x32_bf16 v[76:79], v[164:167], v[236:239], v[76:79]
	v_mfma_f32_16x16x32_bf16 v[124:127], v[160:163], v[216:219], v[124:127]
	v_mfma_f32_16x16x32_bf16 v[120:123], v[168:171], v[216:219], v[120:123]
	v_mfma_f32_16x16x32_bf16 v[116:119], v[160:163], v[224:227], v[116:119]
	v_mfma_f32_16x16x32_bf16 v[108:111], v[168:171], v[224:227], v[108:111]
	v_mfma_f32_16x16x32_bf16 v[100:103], v[160:163], v[232:235], v[100:103]
	v_mfma_f32_16x16x32_bf16 v[92:95], v[168:171], v[232:235], v[92:95]
	v_mfma_f32_16x16x32_bf16 v[84:87], v[160:163], v[240:243], v[84:87]
	v_mfma_f32_16x16x32_bf16 v[76:79], v[168:171], v[240:243], v[76:79]
	s_setprio 0
	s_setprio 1
	v_mfma_f32_16x16x32_bf16 v[112:115], v[172:175], v[212:215], v[112:115]
	v_mfma_f32_16x16x32_bf16 v[104:107], v[204:207], v[212:215], v[104:107]
	v_mfma_f32_16x16x32_bf16 v[96:99], v[172:175], v[220:223], v[96:99]
	v_mfma_f32_16x16x32_bf16 v[88:91], v[204:207], v[220:223], v[88:91]
	v_mfma_f32_16x16x32_bf16 v[80:83], v[172:175], v[228:231], v[80:83]
	v_mfma_f32_16x16x32_bf16 v[72:75], v[204:207], v[228:231], v[72:75]
	v_mfma_f32_16x16x32_bf16 v[68:71], v[172:175], v[236:239], v[68:71]
	v_mfma_f32_16x16x32_bf16 v[64:67], v[204:207], v[236:239], v[64:67]
	v_mfma_f32_16x16x32_bf16 v[112:115], v[176:179], v[216:219], v[112:115]
	v_mfma_f32_16x16x32_bf16 v[104:107], v[208:211], v[216:219], v[104:107]
	v_mfma_f32_16x16x32_bf16 v[96:99], v[176:179], v[224:227], v[96:99]
	v_mfma_f32_16x16x32_bf16 v[88:91], v[208:211], v[224:227], v[88:91]
	v_mfma_f32_16x16x32_bf16 v[80:83], v[176:179], v[232:235], v[80:83]
	v_mfma_f32_16x16x32_bf16 v[72:75], v[208:211], v[232:235], v[72:75]
	v_mfma_f32_16x16x32_bf16 v[68:71], v[176:179], v[240:243], v[68:71]
	v_mfma_f32_16x16x32_bf16 v[64:67], v[208:211], v[240:243], v[64:67]
	s_setprio 0
	s_barrier
	s_add_i32 s18, s58, s36
	v_lshl_add_u64 v[140:141], v[140:141], 0, s[48:49]
	s_mov_b32 m0, s18
	ds_read_b128 v[212:215], v154 offset:49152
	ds_read_b128 v[216:219], v154 offset:50176
	ds_read_b128 v[220:223], v154 offset:51200
	ds_read_b128 v[224:227], v154 offset:52224
	ds_read_b128 v[228:231], v154 offset:53248
	ds_read_b128 v[232:235], v154 offset:54272
	ds_read_b128 v[236:239], v154 offset:55296
	ds_read_b128 v[240:243], v154 offset:56320
	s_add_i32 m0, s18, 0x2000
	s_add_u32 s18, s22, 0xb0080
	v_lshl_add_u64 v[140:141], v[180:181], 0, s[48:49]
	s_addc_u32 s19, s23, 0
	s_add_i32 s22, s59, s36
	v_lshl_add_u64 v[140:141], s[18:19], 0, v[130:131]
	s_mov_b32 m0, s22
	s_nop 0
	v_lshl_add_u64 v[140:141], s[18:19], 0, v[134:135]
	s_add_i32 m0, s22, 0x2000
	s_nop 0
	v_lshl_add_u64 v[140:141], v[244:245], 0, s[48:49]
	s_mov_b32 m0, s43
	s_nop 0
	v_lshl_add_u64 v[140:141], v[246:247], 0, s[48:49]
	s_mov_b32 m0, s44
	s_nop 0
	s_waitcnt vmcnt(0)
	s_waitcnt lgkmcnt(0)
	s_barrier
	s_setprio 1
	s_waitcnt lgkmcnt(0)
	v_mfma_f32_16x16x32_bf16 v[60:63], v[156:159], v[212:215], v[60:63]
	v_mfma_f32_16x16x32_bf16 v[56:59], v[164:167], v[212:215], v[56:59]
	v_mfma_f32_16x16x32_bf16 v[52:55], v[156:159], v[220:223], v[52:55]
	v_mfma_f32_16x16x32_bf16 v[44:47], v[164:167], v[220:223], v[44:47]
	v_mfma_f32_16x16x32_bf16 v[36:39], v[156:159], v[228:231], v[36:39]
	v_mfma_f32_16x16x32_bf16 v[28:31], v[164:167], v[228:231], v[28:31]
	v_mfma_f32_16x16x32_bf16 v[20:23], v[156:159], v[236:239], v[20:23]
	v_mfma_f32_16x16x32_bf16 v[12:15], v[164:167], v[236:239], v[12:15]
	v_mfma_f32_16x16x32_bf16 v[60:63], v[160:163], v[216:219], v[60:63]
	v_mfma_f32_16x16x32_bf16 v[56:59], v[168:171], v[216:219], v[56:59]
	v_mfma_f32_16x16x32_bf16 v[52:55], v[160:163], v[224:227], v[52:55]
	v_mfma_f32_16x16x32_bf16 v[44:47], v[168:171], v[224:227], v[44:47]
	v_mfma_f32_16x16x32_bf16 v[36:39], v[160:163], v[232:235], v[36:39]
	v_mfma_f32_16x16x32_bf16 v[28:31], v[168:171], v[232:235], v[28:31]
	v_mfma_f32_16x16x32_bf16 v[20:23], v[160:163], v[240:243], v[20:23]
	v_mfma_f32_16x16x32_bf16 v[12:15], v[168:171], v[240:243], v[12:15]
	s_setprio 0
	s_setprio 1
	v_mfma_f32_16x16x32_bf16 v[48:51], v[172:175], v[212:215], v[48:51]
	v_mfma_f32_16x16x32_bf16 v[40:43], v[204:207], v[212:215], v[40:43]
	v_mfma_f32_16x16x32_bf16 v[32:35], v[172:175], v[220:223], v[32:35]
	v_mfma_f32_16x16x32_bf16 v[24:27], v[204:207], v[220:223], v[24:27]
	v_mfma_f32_16x16x32_bf16 v[16:19], v[172:175], v[228:231], v[16:19]
	v_mfma_f32_16x16x32_bf16 v[8:11], v[204:207], v[228:231], v[8:11]
	v_mfma_f32_16x16x32_bf16 v[4:7], v[172:175], v[236:239], v[4:7]
	v_mfma_f32_16x16x32_bf16 v[0:3], v[204:207], v[236:239], v[0:3]
	v_mfma_f32_16x16x32_bf16 v[48:51], v[176:179], v[216:219], v[48:51]
	v_mfma_f32_16x16x32_bf16 v[40:43], v[208:211], v[216:219], v[40:43]
	v_mfma_f32_16x16x32_bf16 v[32:35], v[176:179], v[224:227], v[32:35]
	v_mfma_f32_16x16x32_bf16 v[24:27], v[208:211], v[224:227], v[24:27]
	v_mfma_f32_16x16x32_bf16 v[16:19], v[176:179], v[232:235], v[16:19]
	v_mfma_f32_16x16x32_bf16 v[8:11], v[208:211], v[232:235], v[8:11]
	v_mfma_f32_16x16x32_bf16 v[4:7], v[176:179], v[240:243], v[4:7]
	v_mfma_f32_16x16x32_bf16 v[0:3], v[208:211], v[240:243], v[0:3]
	s_setprio 0
	s_barrier
	s_add_i32 s57, s57, 2
	s_add_u32 s17, s17, 0x100
	s_addc_u32 s56, s56, 0
	s_cmp_gt_u32 s57, 19
	s_mov_b64 s[18:19], s[20:21]
.Lpfo_after:
	s_and_b64 vcc, exec, s[12:13]
	s_cbranch_vccz .LBB0_462
	s_barrier

.LBB0_594:
	s_cmp_lg_u32 s36, 12
	s_cbranch_scc1 .Lpmi_body
	s_cmp_eq_u32 s10, 0
	s_cbranch_scc1 .Lpmi_tail
.Lpmi_body:
	s_add_u32 s37, s4, 0xfffc0080
	s_addc_u32 s38, s5, -1
	s_add_i32 s40, 0, 0x10000
	s_cmp_eq_u32 s36, 12
	s_cselect_b32 s55, s7, s38
	s_cselect_b32 s54, s9, s37
	v_add_u32_e32 v144, s40, v141
	s_cselect_b32 s43, s26, s31
	s_cselect_b32 s42, s27, s30
	s_add_i32 s37, 0, 0x14000
	ds_read_b128 v[128:131], v144
	ds_read_b128 v[166:169], v144 offset:1024
	ds_read_b128 v[170:173], v144 offset:2048
	ds_read_b128 v[174:177], v144 offset:3072
	v_add_u32_e32 v144, s37, v141
	ds_read_b128 v[178:181], v144
	ds_read_b128 v[204:207], v144 offset:1024
	ds_read_b128 v[208:211], v144 offset:2048
	ds_read_b128 v[212:215], v144 offset:3072
	v_lshl_add_u64 v[248:249], s[4:5], 0, v[162:163]
	s_add_i32 m0, s87, 0xc000
	ds_read_b128 v[216:219], v155
	ds_read_b128 v[220:223], v155 offset:1024
	ds_read_b128 v[224:227], v155 offset:2048
	ds_read_b128 v[228:231], v155 offset:3072
	ds_read_b128 v[232:235], v155 offset:4096
	ds_read_b128 v[236:239], v155 offset:5120
	ds_read_b128 v[240:243], v155 offset:6144
	ds_read_b128 v[244:247], v155 offset:7168
	global_load_lds_dwordx4 v[248:249], off
	v_lshl_add_u64 v[248:249], s[4:5], 0, v[164:165]
	s_add_i32 m0, s87, 0xe000
	s_nop 0
	global_load_lds_dwordx4 v[248:249], off
	s_waitcnt vmcnt(8)
	s_waitcnt lgkmcnt(0)
	s_barrier
	s_setprio 1
	s_waitcnt lgkmcnt(0)
	v_mfma_f32_16x16x32_bf16 v[124:127], v[128:131], v[216:219], v[124:127]
	v_mfma_f32_16x16x32_bf16 v[120:123], v[170:173], v[216:219], v[120:123]
	v_mfma_f32_16x16x32_bf16 v[108:111], v[128:131], v[224:227], v[108:111]
	v_mfma_f32_16x16x32_bf16 v[104:107], v[170:173], v[224:227], v[104:107]
	v_mfma_f32_16x16x32_bf16 v[92:95], v[128:131], v[232:235], v[92:95]
	v_mfma_f32_16x16x32_bf16 v[88:91], v[170:173], v[232:235], v[88:91]
	v_mfma_f32_16x16x32_bf16 v[76:79], v[128:131], v[240:243], v[76:79]
	v_mfma_f32_16x16x32_bf16 v[72:75], v[170:173], v[240:243], v[72:75]
	v_mfma_f32_16x16x32_bf16 v[124:127], v[166:169], v[220:223], v[124:127]
	v_mfma_f32_16x16x32_bf16 v[120:123], v[174:177], v[220:223], v[120:123]
	v_mfma_f32_16x16x32_bf16 v[108:111], v[166:169], v[228:231], v[108:111]
	v_mfma_f32_16x16x32_bf16 v[104:107], v[174:177], v[228:231], v[104:107]
	v_mfma_f32_16x16x32_bf16 v[92:95], v[166:169], v[236:239], v[92:95]
	v_mfma_f32_16x16x32_bf16 v[88:91], v[174:177], v[236:239], v[88:91]
	v_mfma_f32_16x16x32_bf16 v[76:79], v[166:169], v[244:247], v[76:79]
	v_mfma_f32_16x16x32_bf16 v[72:75], v[174:177], v[244:247], v[72:75]
	s_setprio 0
	s_setprio 1
	v_mfma_f32_16x16x32_bf16 v[116:119], v[178:181], v[216:219], v[116:119]
	v_mfma_f32_16x16x32_bf16 v[112:115], v[208:211], v[216:219], v[112:115]
	v_mfma_f32_16x16x32_bf16 v[100:103], v[178:181], v[224:227], v[100:103]
	v_mfma_f32_16x16x32_bf16 v[96:99], v[208:211], v[224:227], v[96:99]
	v_mfma_f32_16x16x32_bf16 v[84:87], v[178:181], v[232:235], v[84:87]
	v_mfma_f32_16x16x32_bf16 v[80:83], v[208:211], v[232:235], v[80:83]
	v_mfma_f32_16x16x32_bf16 v[68:71], v[178:181], v[240:243], v[68:71]
	v_mfma_f32_16x16x32_bf16 v[64:67], v[208:211], v[240:243], v[64:67]
	v_mfma_f32_16x16x32_bf16 v[116:119], v[204:207], v[220:223], v[116:119]
	v_mfma_f32_16x16x32_bf16 v[112:115], v[212:215], v[220:223], v[112:115]
	v_mfma_f32_16x16x32_bf16 v[100:103], v[204:207], v[228:231], v[100:103]
	v_mfma_f32_16x16x32_bf16 v[96:99], v[212:215], v[228:231], v[96:99]
	v_mfma_f32_16x16x32_bf16 v[84:87], v[204:207], v[236:239], v[84:87]
	v_mfma_f32_16x16x32_bf16 v[80:83], v[212:215], v[236:239], v[80:83]
	v_mfma_f32_16x16x32_bf16 v[68:71], v[204:207], v[244:247], v[68:71]
	v_mfma_f32_16x16x32_bf16 v[64:67], v[212:215], v[244:247], v[64:67]
	s_setprio 0
	s_barrier
	s_add_i32 s38, s40, s86
	v_lshl_add_u64 v[248:249], s[42:43], 0, v[134:135]
	s_mov_b32 m0, s38
	ds_read_b128 v[216:219], v155 offset:16384
	ds_read_b128 v[220:223], v155 offset:17408
	ds_read_b128 v[224:227], v155 offset:18432
	ds_read_b128 v[228:231], v155 offset:19456
	ds_read_b128 v[232:235], v155 offset:20480
	ds_read_b128 v[236:239], v155 offset:21504
	ds_read_b128 v[240:243], v155 offset:22528
	ds_read_b128 v[244:247], v155 offset:23552
	global_load_lds_dwordx4 v[248:249], off
	s_add_i32 m0, s38, 0x2000
	s_add_u32 s44, s42, 0x40000
	v_lshl_add_u64 v[250:251], s[42:43], 0, v[138:139]
	s_addc_u32 s45, s43, 0
	s_add_i32 s37, s37, s86
	global_load_lds_dwordx4 v[250:251], off
	v_lshl_add_u64 v[252:253], s[44:45], 0, v[134:135]
	s_mov_b32 m0, s37
	v_lshl_add_u64 v[190:191], s[54:55], 0, v[136:137]
	global_load_lds_dwordx4 v[252:253], off
	v_lshl_add_u64 v[252:253], s[44:45], 0, v[138:139]
	s_add_i32 m0, s37, 0x2000
	s_nop 0
	global_load_lds_dwordx4 v[252:253], off
	v_lshl_add_u64 v[252:253], s[54:55], 0, v[132:133]
	s_mov_b32 m0, s87
	s_nop 0
	global_load_lds_dwordx4 v[252:253], off
	s_mov_b32 m0, s76
	s_nop 0
	global_load_lds_dwordx4 v[190:191], off
	s_waitcnt vmcnt(8)
	s_waitcnt lgkmcnt(0)
	s_barrier
	s_setprio 1
	s_waitcnt lgkmcnt(0)
	v_mfma_f32_16x16x32_bf16 v[60:63], v[128:131], v[216:219], v[60:63]
	v_mfma_f32_16x16x32_bf16 v[56:59], v[170:173], v[216:219], v[56:59]
	v_mfma_f32_16x16x32_bf16 v[44:47], v[128:131], v[224:227], v[44:47]
	v_mfma_f32_16x16x32_bf16 v[40:43], v[170:173], v[224:227], v[40:43]
	v_mfma_f32_16x16x32_bf16 v[28:31], v[128:131], v[232:235], v[28:31]
	v_mfma_f32_16x16x32_bf16 v[24:27], v[170:173], v[232:235], v[24:27]
	v_mfma_f32_16x16x32_bf16 v[12:15], v[128:131], v[240:243], v[12:15]
	v_mfma_f32_16x16x32_bf16 v[8:11], v[170:173], v[240:243], v[8:11]
	v_mfma_f32_16x16x32_bf16 v[60:63], v[166:169], v[220:223], v[60:63]
	v_mfma_f32_16x16x32_bf16 v[56:59], v[174:177], v[220:223], v[56:59]
	v_mfma_f32_16x16x32_bf16 v[44:47], v[166:169], v[228:231], v[44:47]
	v_mfma_f32_16x16x32_bf16 v[40:43], v[174:177], v[228:231], v[40:43]
	v_mfma_f32_16x16x32_bf16 v[28:31], v[166:169], v[236:239], v[28:31]
	v_mfma_f32_16x16x32_bf16 v[24:27], v[174:177], v[236:239], v[24:27]
	v_mfma_f32_16x16x32_bf16 v[12:15], v[166:169], v[244:247], v[12:15]
	v_mfma_f32_16x16x32_bf16 v[8:11], v[174:177], v[244:247], v[8:11]
	s_setprio 0
	s_setprio 1
	v_mfma_f32_16x16x32_bf16 v[52:55], v[178:181], v[216:219], v[52:55]
	v_mfma_f32_16x16x32_bf16 v[48:51], v[208:211], v[216:219], v[48:51]
	v_mfma_f32_16x16x32_bf16 v[36:39], v[178:181], v[224:227], v[36:39]
	v_mfma_f32_16x16x32_bf16 v[32:35], v[208:211], v[224:227], v[32:35]
	v_mfma_f32_16x16x32_bf16 v[20:23], v[178:181], v[232:235], v[20:23]
	v_mfma_f32_16x16x32_bf16 v[16:19], v[208:211], v[232:235], v[16:19]
	v_mfma_f32_16x16x32_bf16 v[4:7], v[178:181], v[240:243], v[4:7]
	v_mfma_f32_16x16x32_bf16 v[0:3], v[208:211], v[240:243], v[0:3]
	v_mfma_f32_16x16x32_bf16 v[52:55], v[204:207], v[220:223], v[52:55]
	v_mfma_f32_16x16x32_bf16 v[48:51], v[212:215], v[220:223], v[48:51]
	v_mfma_f32_16x16x32_bf16 v[36:39], v[204:207], v[228:231], v[36:39]
	v_mfma_f32_16x16x32_bf16 v[32:35], v[212:215], v[228:231], v[32:35]
	v_mfma_f32_16x16x32_bf16 v[20:23], v[204:207], v[236:239], v[20:23]
	v_mfma_f32_16x16x32_bf16 v[16:19], v[212:215], v[236:239], v[16:19]
	v_mfma_f32_16x16x32_bf16 v[4:7], v[204:207], v[244:247], v[4:7]
	v_mfma_f32_16x16x32_bf16 v[0:3], v[212:215], v[244:247], v[0:3]
	s_setprio 0
	s_barrier
	s_add_i32 s37, 0, 0x18000
	v_add_u32_e32 v144, s37, v141
	s_add_i32 s38, 0, 0x1c000
	ds_read_b128 v[128:131], v144
	ds_read_b128 v[166:169], v144 offset:1024
	ds_read_b128 v[170:173], v144 offset:2048
	ds_read_b128 v[174:177], v144 offset:3072
	v_add_u32_e32 v144, s38, v141
	ds_read_b128 v[178:181], v144
	ds_read_b128 v[204:207], v144 offset:1024
	ds_read_b128 v[208:211], v144 offset:2048
	ds_read_b128 v[212:215], v144 offset:3072
	s_add_u32 s44, s54, 0x40000
	s_addc_u32 s45, s55, 0
	s_mov_b32 m0, s77
	v_lshl_add_u64 v[192:193], s[44:45], 0, v[132:133]
	ds_read_b128 v[216:219], v155 offset:32768
	ds_read_b128 v[220:223], v155 offset:33792
	ds_read_b128 v[224:227], v155 offset:34816
	ds_read_b128 v[228:231], v155 offset:35840
	ds_read_b128 v[232:235], v155 offset:36864
	ds_read_b128 v[236:239], v155 offset:37888
	ds_read_b128 v[240:243], v155 offset:38912
	ds_read_b128 v[244:247], v155 offset:39936
	global_load_lds_dwordx4 v[192:193], off
	v_lshl_add_u64 v[192:193], s[44:45], 0, v[136:137]
	s_mov_b32 m0, s74
	s_nop 0
	global_load_lds_dwordx4 v[192:193], off
	s_waitcnt vmcnt(8)
	s_waitcnt lgkmcnt(0)
	s_barrier
	s_setprio 1
	s_waitcnt lgkmcnt(0)
	v_mfma_f32_16x16x32_bf16 v[124:127], v[128:131], v[216:219], v[124:127]
	v_mfma_f32_16x16x32_bf16 v[120:123], v[170:173], v[216:219], v[120:123]
	v_mfma_f32_16x16x32_bf16 v[108:111], v[128:131], v[224:227], v[108:111]
	v_mfma_f32_16x16x32_bf16 v[104:107], v[170:173], v[224:227], v[104:107]
	v_mfma_f32_16x16x32_bf16 v[92:95], v[128:131], v[232:235], v[92:95]
	v_mfma_f32_16x16x32_bf16 v[88:91], v[170:173], v[232:235], v[88:91]
	v_mfma_f32_16x16x32_bf16 v[76:79], v[128:131], v[240:243], v[76:79]
	v_mfma_f32_16x16x32_bf16 v[72:75], v[170:173], v[240:243], v[72:75]
	v_mfma_f32_16x16x32_bf16 v[124:127], v[166:169], v[220:223], v[124:127]
	v_mfma_f32_16x16x32_bf16 v[120:123], v[174:177], v[220:223], v[120:123]
	v_mfma_f32_16x16x32_bf16 v[108:111], v[166:169], v[228:231], v[108:111]
	v_mfma_f32_16x16x32_bf16 v[104:107], v[174:177], v[228:231], v[104:107]
	v_mfma_f32_16x16x32_bf16 v[92:95], v[166:169], v[236:239], v[92:95]
	v_mfma_f32_16x16x32_bf16 v[88:91], v[174:177], v[236:239], v[88:91]
	v_mfma_f32_16x16x32_bf16 v[76:79], v[166:169], v[244:247], v[76:79]
	v_mfma_f32_16x16x32_bf16 v[72:75], v[174:177], v[244:247], v[72:75]
	s_setprio 0
	s_setprio 1
	v_mfma_f32_16x16x32_bf16 v[116:119], v[178:181], v[216:219], v[116:119]
	v_mfma_f32_16x16x32_bf16 v[112:115], v[208:211], v[216:219], v[112:115]
	v_mfma_f32_16x16x32_bf16 v[100:103], v[178:181], v[224:227], v[100:103]
	v_mfma_f32_16x16x32_bf16 v[96:99], v[208:211], v[224:227], v[96:99]
	v_mfma_f32_16x16x32_bf16 v[84:87], v[178:181], v[232:235], v[84:87]
	v_mfma_f32_16x16x32_bf16 v[80:83], v[208:211], v[232:235], v[80:83]
	v_mfma_f32_16x16x32_bf16 v[68:71], v[178:181], v[240:243], v[68:71]
	v_mfma_f32_16x16x32_bf16 v[64:67], v[208:211], v[240:243], v[64:67]
	v_mfma_f32_16x16x32_bf16 v[116:119], v[204:207], v[220:223], v[116:119]
	v_mfma_f32_16x16x32_bf16 v[112:115], v[212:215], v[220:223], v[112:115]
	v_mfma_f32_16x16x32_bf16 v[100:103], v[204:207], v[228:231], v[100:103]
	v_mfma_f32_16x16x32_bf16 v[96:99], v[212:215], v[228:231], v[96:99]
	v_mfma_f32_16x16x32_bf16 v[84:87], v[204:207], v[236:239], v[84:87]
	v_mfma_f32_16x16x32_bf16 v[80:83], v[212:215], v[236:239], v[80:83]
	v_mfma_f32_16x16x32_bf16 v[68:71], v[204:207], v[244:247], v[68:71]
	v_mfma_f32_16x16x32_bf16 v[64:67], v[212:215], v[244:247], v[64:67]
	s_setprio 0
	s_barrier
	s_add_i32 s37, s37, s86
	v_lshl_add_u64 v[192:193], v[248:249], 0, s[48:49]
	s_mov_b32 m0, s37
	ds_read_b128 v[216:219], v155 offset:49152
	ds_read_b128 v[220:223], v155 offset:50176
	ds_read_b128 v[224:227], v155 offset:51200
	ds_read_b128 v[228:231], v155 offset:52224
	ds_read_b128 v[232:235], v155 offset:53248
	ds_read_b128 v[236:239], v155 offset:54272
	ds_read_b128 v[240:243], v155 offset:55296
	ds_read_b128 v[244:247], v155 offset:56320
	global_load_lds_dwordx4 v[192:193], off
	s_add_i32 m0, s37, 0x2000
	s_add_u32 s42, s42, 0x40080
	v_lshl_add_u64 v[192:193], v[250:251], 0, s[48:49]
	s_addc_u32 s43, s43, 0
	s_add_i32 s37, s38, s86
	global_load_lds_dwordx4 v[192:193], off
	v_lshl_add_u64 v[192:193], s[42:43], 0, v[134:135]
	s_mov_b32 m0, s37
	v_lshl_add_u64 v[190:191], v[190:191], 0, s[48:49]
	global_load_lds_dwordx4 v[192:193], off
	v_lshl_add_u64 v[192:193], s[42:43], 0, v[138:139]
	s_add_i32 m0, s37, 0x2000
	s_nop 0
	global_load_lds_dwordx4 v[192:193], off
	v_lshl_add_u64 v[192:193], v[252:253], 0, s[48:49]
	s_mov_b32 m0, s82
	s_nop 0
	global_load_lds_dwordx4 v[192:193], off
	s_mov_b32 m0, s83
	s_nop 0
	global_load_lds_dwordx4 v[190:191], off
	s_waitcnt vmcnt(8)
	s_waitcnt lgkmcnt(0)
	s_barrier
	s_setprio 1
	s_waitcnt lgkmcnt(0)
	v_mfma_f32_16x16x32_bf16 v[60:63], v[128:131], v[216:219], v[60:63]
	v_mfma_f32_16x16x32_bf16 v[56:59], v[170:173], v[216:219], v[56:59]
	v_mfma_f32_16x16x32_bf16 v[44:47], v[128:131], v[224:227], v[44:47]
	v_mfma_f32_16x16x32_bf16 v[40:43], v[170:173], v[224:227], v[40:43]
	v_mfma_f32_16x16x32_bf16 v[28:31], v[128:131], v[232:235], v[28:31]
	v_mfma_f32_16x16x32_bf16 v[24:27], v[170:173], v[232:235], v[24:27]
	v_mfma_f32_16x16x32_bf16 v[12:15], v[128:131], v[240:243], v[12:15]
	v_mfma_f32_16x16x32_bf16 v[8:11], v[170:173], v[240:243], v[8:11]
	v_mfma_f32_16x16x32_bf16 v[60:63], v[166:169], v[220:223], v[60:63]
	v_mfma_f32_16x16x32_bf16 v[56:59], v[174:177], v[220:223], v[56:59]
	v_mfma_f32_16x16x32_bf16 v[44:47], v[166:169], v[228:231], v[44:47]
	v_mfma_f32_16x16x32_bf16 v[40:43], v[174:177], v[228:231], v[40:43]
	v_mfma_f32_16x16x32_bf16 v[28:31], v[166:169], v[236:239], v[28:31]
	v_mfma_f32_16x16x32_bf16 v[24:27], v[174:177], v[236:239], v[24:27]
	v_mfma_f32_16x16x32_bf16 v[12:15], v[166:169], v[244:247], v[12:15]
	v_mfma_f32_16x16x32_bf16 v[8:11], v[174:177], v[244:247], v[8:11]
	s_setprio 0
	s_setprio 1
	v_mfma_f32_16x16x32_bf16 v[52:55], v[178:181], v[216:219], v[52:55]
	v_mfma_f32_16x16x32_bf16 v[48:51], v[208:211], v[216:219], v[48:51]
	v_mfma_f32_16x16x32_bf16 v[36:39], v[178:181], v[224:227], v[36:39]
	v_mfma_f32_16x16x32_bf16 v[32:35], v[208:211], v[224:227], v[32:35]
	v_mfma_f32_16x16x32_bf16 v[20:23], v[178:181], v[232:235], v[20:23]
	v_mfma_f32_16x16x32_bf16 v[16:19], v[208:211], v[232:235], v[16:19]
	v_mfma_f32_16x16x32_bf16 v[4:7], v[178:181], v[240:243], v[4:7]
	v_mfma_f32_16x16x32_bf16 v[0:3], v[208:211], v[240:243], v[0:3]
	v_mfma_f32_16x16x32_bf16 v[52:55], v[204:207], v[220:223], v[52:55]
	v_mfma_f32_16x16x32_bf16 v[48:51], v[212:215], v[220:223], v[48:51]
	v_mfma_f32_16x16x32_bf16 v[36:39], v[204:207], v[228:231], v[36:39]
	v_mfma_f32_16x16x32_bf16 v[32:35], v[212:215], v[228:231], v[32:35]
	v_mfma_f32_16x16x32_bf16 v[20:23], v[204:207], v[236:239], v[20:23]
	v_mfma_f32_16x16x32_bf16 v[16:19], v[212:215], v[236:239], v[16:19]
	v_mfma_f32_16x16x32_bf16 v[4:7], v[204:207], v[244:247], v[4:7]
	v_mfma_f32_16x16x32_bf16 v[0:3], v[212:215], v[244:247], v[0:3]
	s_setprio 0
	s_barrier
	s_add_i32 s36, s36, 2
	s_add_u32 s4, s4, 0x100
	s_addc_u32 s5, s5, 0
	s_add_u32 s30, s30, 0x100
	s_addc_u32 s31, s31, 0
	s_cmp_gt_u32 s36, 13
	s_cbranch_scc0 .LBB0_594
	s_branch .Lpmi_after
.Lpmi_tail:
	s_add_u32 s37, s4, 0xfffc0080
	s_addc_u32 s38, s5, -1
	s_add_i32 s40, 0, 0x10000
	s_cmp_eq_u32 s36, 12
	s_cselect_b32 s55, s7, s38
	s_cselect_b32 s54, s9, s37
	v_add_u32_e32 v144, s40, v141
	s_cselect_b32 s43, s26, s31
	s_cselect_b32 s42, s27, s30
	s_add_i32 s37, 0, 0x14000
	ds_read_b128 v[128:131], v144
	ds_read_b128 v[166:169], v144 offset:1024
	ds_read_b128 v[170:173], v144 offset:2048
	ds_read_b128 v[174:177], v144 offset:3072
	v_add_u32_e32 v144, s37, v141
	ds_read_b128 v[178:181], v144
	ds_read_b128 v[204:207], v144 offset:1024
	ds_read_b128 v[208:211], v144 offset:2048
	ds_read_b128 v[212:215], v144 offset:3072
	v_lshl_add_u64 v[248:249], s[4:5], 0, v[162:163]
	s_add_i32 m0, s87, 0xc000
	ds_read_b128 v[216:219], v155
	ds_read_b128 v[220:223], v155 offset:1024
	ds_read_b128 v[224:227], v155 offset:2048
	ds_read_b128 v[228:231], v155 offset:3072
	ds_read_b128 v[232:235], v155 offset:4096
	ds_read_b128 v[236:239], v155 offset:5120
	ds_read_b128 v[240:243], v155 offset:6144
	ds_read_b128 v[244:247], v155 offset:7168
	global_load_lds_dwordx4 v[248:249], off
	v_lshl_add_u64 v[248:249], s[4:5], 0, v[164:165]
	s_add_i32 m0, s87, 0xe000
	s_nop 0
	global_load_lds_dwordx4 v[248:249], off
	s_waitcnt vmcnt(8)
	s_waitcnt lgkmcnt(0)
	s_barrier
	s_setprio 1
	s_waitcnt lgkmcnt(0)
	v_mfma_f32_16x16x32_bf16 v[124:127], v[128:131], v[216:219], v[124:127]
	v_mfma_f32_16x16x32_bf16 v[120:123], v[170:173], v[216:219], v[120:123]
	v_mfma_f32_16x16x32_bf16 v[108:111], v[128:131], v[224:227], v[108:111]
	v_mfma_f32_16x16x32_bf16 v[104:107], v[170:173], v[224:227], v[104:107]
	v_mfma_f32_16x16x32_bf16 v[92:95], v[128:131], v[232:235], v[92:95]
	v_mfma_f32_16x16x32_bf16 v[88:91], v[170:173], v[232:235], v[88:91]
	v_mfma_f32_16x16x32_bf16 v[76:79], v[128:131], v[240:243], v[76:79]
	v_mfma_f32_16x16x32_bf16 v[72:75], v[170:173], v[240:243], v[72:75]
	v_mfma_f32_16x16x32_bf16 v[124:127], v[166:169], v[220:223], v[124:127]
	v_mfma_f32_16x16x32_bf16 v[120:123], v[174:177], v[220:223], v[120:123]
	v_mfma_f32_16x16x32_bf16 v[108:111], v[166:169], v[228:231], v[108:111]
	v_mfma_f32_16x16x32_bf16 v[104:107], v[174:177], v[228:231], v[104:107]
	v_mfma_f32_16x16x32_bf16 v[92:95], v[166:169], v[236:239], v[92:95]
	v_mfma_f32_16x16x32_bf16 v[88:91], v[174:177], v[236:239], v[88:91]
	v_mfma_f32_16x16x32_bf16 v[76:79], v[166:169], v[244:247], v[76:79]
	v_mfma_f32_16x16x32_bf16 v[72:75], v[174:177], v[244:247], v[72:75]
	s_setprio 0
	s_setprio 1
	v_mfma_f32_16x16x32_bf16 v[116:119], v[178:181], v[216:219], v[116:119]
	v_mfma_f32_16x16x32_bf16 v[112:115], v[208:211], v[216:219], v[112:115]
	v_mfma_f32_16x16x32_bf16 v[100:103], v[178:181], v[224:227], v[100:103]
	v_mfma_f32_16x16x32_bf16 v[96:99], v[208:211], v[224:227], v[96:99]
	v_mfma_f32_16x16x32_bf16 v[84:87], v[178:181], v[232:235], v[84:87]
	v_mfma_f32_16x16x32_bf16 v[80:83], v[208:211], v[232:235], v[80:83]
	v_mfma_f32_16x16x32_bf16 v[68:71], v[178:181], v[240:243], v[68:71]
	v_mfma_f32_16x16x32_bf16 v[64:67], v[208:211], v[240:243], v[64:67]
	v_mfma_f32_16x16x32_bf16 v[116:119], v[204:207], v[220:223], v[116:119]
	v_mfma_f32_16x16x32_bf16 v[112:115], v[212:215], v[220:223], v[112:115]
	v_mfma_f32_16x16x32_bf16 v[100:103], v[204:207], v[228:231], v[100:103]
	v_mfma_f32_16x16x32_bf16 v[96:99], v[212:215], v[228:231], v[96:99]
	v_mfma_f32_16x16x32_bf16 v[84:87], v[204:207], v[236:239], v[84:87]
	v_mfma_f32_16x16x32_bf16 v[80:83], v[212:215], v[236:239], v[80:83]
	v_mfma_f32_16x16x32_bf16 v[68:71], v[204:207], v[244:247], v[68:71]
	v_mfma_f32_16x16x32_bf16 v[64:67], v[212:215], v[244:247], v[64:67]
	s_setprio 0
	s_barrier
	s_add_i32 s38, s40, s86
	v_lshl_add_u64 v[248:249], s[42:43], 0, v[134:135]
	s_mov_b32 m0, s38
	ds_read_b128 v[216:219], v155 offset:16384
	ds_read_b128 v[220:223], v155 offset:17408
	ds_read_b128 v[224:227], v155 offset:18432
	ds_read_b128 v[228:231], v155 offset:19456
	ds_read_b128 v[232:235], v155 offset:20480
	ds_read_b128 v[236:239], v155 offset:21504
	ds_read_b128 v[240:243], v155 offset:22528
	ds_read_b128 v[244:247], v155 offset:23552
	s_add_i32 m0, s38, 0x2000
	s_add_u32 s44, s42, 0x40000
	v_lshl_add_u64 v[250:251], s[42:43], 0, v[138:139]
	s_addc_u32 s45, s43, 0
	s_add_i32 s37, s37, s86
	v_lshl_add_u64 v[252:253], s[44:45], 0, v[134:135]
	s_mov_b32 m0, s37
	v_lshl_add_u64 v[190:191], s[54:55], 0, v[136:137]
	v_lshl_add_u64 v[252:253], s[44:45], 0, v[138:139]
	s_add_i32 m0, s37, 0x2000
	s_nop 0
	v_lshl_add_u64 v[252:253], s[54:55], 0, v[132:133]
	s_mov_b32 m0, s87
	s_nop 0
	s_mov_b32 m0, s76
	s_nop 0
	s_waitcnt vmcnt(2)
	s_waitcnt lgkmcnt(0)
	s_barrier
	s_setprio 1
	s_waitcnt lgkmcnt(0)
	v_mfma_f32_16x16x32_bf16 v[60:63], v[128:131], v[216:219], v[60:63]
	v_mfma_f32_16x16x32_bf16 v[56:59], v[170:173], v[216:219], v[56:59]
	v_mfma_f32_16x16x32_bf16 v[44:47], v[128:131], v[224:227], v[44:47]
	v_mfma_f32_16x16x32_bf16 v[40:43], v[170:173], v[224:227], v[40:43]
	v_mfma_f32_16x16x32_bf16 v[28:31], v[128:131], v[232:235], v[28:31]
	v_mfma_f32_16x16x32_bf16 v[24:27], v[170:173], v[232:235], v[24:27]
	v_mfma_f32_16x16x32_bf16 v[12:15], v[128:131], v[240:243], v[12:15]
	v_mfma_f32_16x16x32_bf16 v[8:11], v[170:173], v[240:243], v[8:11]
	v_mfma_f32_16x16x32_bf16 v[60:63], v[166:169], v[220:223], v[60:63]
	v_mfma_f32_16x16x32_bf16 v[56:59], v[174:177], v[220:223], v[56:59]
	v_mfma_f32_16x16x32_bf16 v[44:47], v[166:169], v[228:231], v[44:47]
	v_mfma_f32_16x16x32_bf16 v[40:43], v[174:177], v[228:231], v[40:43]
	v_mfma_f32_16x16x32_bf16 v[28:31], v[166:169], v[236:239], v[28:31]
	v_mfma_f32_16x16x32_bf16 v[24:27], v[174:177], v[236:239], v[24:27]
	v_mfma_f32_16x16x32_bf16 v[12:15], v[166:169], v[244:247], v[12:15]
	v_mfma_f32_16x16x32_bf16 v[8:11], v[174:177], v[244:247], v[8:11]
	s_setprio 0
	s_setprio 1
	v_mfma_f32_16x16x32_bf16 v[52:55], v[178:181], v[216:219], v[52:55]
	v_mfma_f32_16x16x32_bf16 v[48:51], v[208:211], v[216:219], v[48:51]
	v_mfma_f32_16x16x32_bf16 v[36:39], v[178:181], v[224:227], v[36:39]
	v_mfma_f32_16x16x32_bf16 v[32:35], v[208:211], v[224:227], v[32:35]
	v_mfma_f32_16x16x32_bf16 v[20:23], v[178:181], v[232:235], v[20:23]
	v_mfma_f32_16x16x32_bf16 v[16:19], v[208:211], v[232:235], v[16:19]
	v_mfma_f32_16x16x32_bf16 v[4:7], v[178:181], v[240:243], v[4:7]
	v_mfma_f32_16x16x32_bf16 v[0:3], v[208:211], v[240:243], v[0:3]
	v_mfma_f32_16x16x32_bf16 v[52:55], v[204:207], v[220:223], v[52:55]
	v_mfma_f32_16x16x32_bf16 v[48:51], v[212:215], v[220:223], v[48:51]
	v_mfma_f32_16x16x32_bf16 v[36:39], v[204:207], v[228:231], v[36:39]
	v_mfma_f32_16x16x32_bf16 v[32:35], v[212:215], v[228:231], v[32:35]
	v_mfma_f32_16x16x32_bf16 v[20:23], v[204:207], v[236:239], v[20:23]
	v_mfma_f32_16x16x32_bf16 v[16:19], v[212:215], v[236:239], v[16:19]
	v_mfma_f32_16x16x32_bf16 v[4:7], v[204:207], v[244:247], v[4:7]
	v_mfma_f32_16x16x32_bf16 v[0:3], v[212:215], v[244:247], v[0:3]
	s_setprio 0
	s_barrier
	s_add_i32 s37, 0, 0x18000
	v_add_u32_e32 v144, s37, v141
	s_add_i32 s38, 0, 0x1c000
	ds_read_b128 v[128:131], v144
	ds_read_b128 v[166:169], v144 offset:1024
	ds_read_b128 v[170:173], v144 offset:2048
	ds_read_b128 v[174:177], v144 offset:3072
	v_add_u32_e32 v144, s38, v141
	ds_read_b128 v[178:181], v144
	ds_read_b128 v[204:207], v144 offset:1024
	ds_read_b128 v[208:211], v144 offset:2048
	ds_read_b128 v[212:215], v144 offset:3072
	s_add_u32 s44, s54, 0x40000
	s_addc_u32 s45, s55, 0
	s_mov_b32 m0, s77
	v_lshl_add_u64 v[192:193], s[44:45], 0, v[132:133]
	ds_read_b128 v[216:219], v155 offset:32768
	ds_read_b128 v[220:223], v155 offset:33792
	ds_read_b128 v[224:227], v155 offset:34816
	ds_read_b128 v[228:231], v155 offset:35840
	ds_read_b128 v[232:235], v155 offset:36864
	ds_read_b128 v[236:239], v155 offset:37888
	ds_read_b128 v[240:243], v155 offset:38912
	ds_read_b128 v[244:247], v155 offset:39936
	v_lshl_add_u64 v[192:193], s[44:45], 0, v[136:137]
	s_mov_b32 m0, s74
	s_nop 0
	s_waitcnt vmcnt(0)
	s_waitcnt lgkmcnt(0)
	s_barrier
	s_setprio 1
	s_waitcnt lgkmcnt(0)
	v_mfma_f32_16x16x32_bf16 v[124:127], v[128:131], v[216:219], v[124:127]
	v_mfma_f32_16x16x32_bf16 v[120:123], v[170:173], v[216:219], v[120:123]
	v_mfma_f32_16x16x32_bf16 v[108:111], v[128:131], v[224:227], v[108:111]
	v_mfma_f32_16x16x32_bf16 v[104:107], v[170:173], v[224:227], v[104:107]
	v_mfma_f32_16x16x32_bf16 v[92:95], v[128:131], v[232:235], v[92:95]
	v_mfma_f32_16x16x32_bf16 v[88:91], v[170:173], v[232:235], v[88:91]
	v_mfma_f32_16x16x32_bf16 v[76:79], v[128:131], v[240:243], v[76:79]
	v_mfma_f32_16x16x32_bf16 v[72:75], v[170:173], v[240:243], v[72:75]
	v_mfma_f32_16x16x32_bf16 v[124:127], v[166:169], v[220:223], v[124:127]
	v_mfma_f32_16x16x32_bf16 v[120:123], v[174:177], v[220:223], v[120:123]
	v_mfma_f32_16x16x32_bf16 v[108:111], v[166:169], v[228:231], v[108:111]
	v_mfma_f32_16x16x32_bf16 v[104:107], v[174:177], v[228:231], v[104:107]
	v_mfma_f32_16x16x32_bf16 v[92:95], v[166:169], v[236:239], v[92:95]
	v_mfma_f32_16x16x32_bf16 v[88:91], v[174:177], v[236:239], v[88:91]
	v_mfma_f32_16x16x32_bf16 v[76:79], v[166:169], v[244:247], v[76:79]
	v_mfma_f32_16x16x32_bf16 v[72:75], v[174:177], v[244:247], v[72:75]
	s_setprio 0
	s_setprio 1
	v_mfma_f32_16x16x32_bf16 v[116:119], v[178:181], v[216:219], v[116:119]
	v_mfma_f32_16x16x32_bf16 v[112:115], v[208:211], v[216:219], v[112:115]
	v_mfma_f32_16x16x32_bf16 v[100:103], v[178:181], v[224:227], v[100:103]
	v_mfma_f32_16x16x32_bf16 v[96:99], v[208:211], v[224:227], v[96:99]
	v_mfma_f32_16x16x32_bf16 v[84:87], v[178:181], v[232:235], v[84:87]
	v_mfma_f32_16x16x32_bf16 v[80:83], v[208:211], v[232:235], v[80:83]
	v_mfma_f32_16x16x32_bf16 v[68:71], v[178:181], v[240:243], v[68:71]
	v_mfma_f32_16x16x32_bf16 v[64:67], v[208:211], v[240:243], v[64:67]
	v_mfma_f32_16x16x32_bf16 v[116:119], v[204:207], v[220:223], v[116:119]
	v_mfma_f32_16x16x32_bf16 v[112:115], v[212:215], v[220:223], v[112:115]
	v_mfma_f32_16x16x32_bf16 v[100:103], v[204:207], v[228:231], v[100:103]
	v_mfma_f32_16x16x32_bf16 v[96:99], v[212:215], v[228:231], v[96:99]
	v_mfma_f32_16x16x32_bf16 v[84:87], v[204:207], v[236:239], v[84:87]
	v_mfma_f32_16x16x32_bf16 v[80:83], v[212:215], v[236:239], v[80:83]
	v_mfma_f32_16x16x32_bf16 v[68:71], v[204:207], v[244:247], v[68:71]
	v_mfma_f32_16x16x32_bf16 v[64:67], v[212:215], v[244:247], v[64:67]
	s_setprio 0
	s_barrier
	s_add_i32 s37, s37, s86
	v_lshl_add_u64 v[192:193], v[248:249], 0, s[48:49]
	s_mov_b32 m0, s37
	ds_read_b128 v[216:219], v155 offset:49152
	ds_read_b128 v[220:223], v155 offset:50176
	ds_read_b128 v[224:227], v155 offset:51200
	ds_read_b128 v[228:231], v155 offset:52224
	ds_read_b128 v[232:235], v155 offset:53248
	ds_read_b128 v[236:239], v155 offset:54272
	ds_read_b128 v[240:243], v155 offset:55296
	ds_read_b128 v[244:247], v155 offset:56320
	s_add_i32 m0, s37, 0x2000
	s_add_u32 s42, s42, 0x40080
	v_lshl_add_u64 v[192:193], v[250:251], 0, s[48:49]
	s_addc_u32 s43, s43, 0
	s_add_i32 s37, s38, s86
	v_lshl_add_u64 v[192:193], s[42:43], 0, v[134:135]
	s_mov_b32 m0, s37
	v_lshl_add_u64 v[190:191], v[190:191], 0, s[48:49]
	v_lshl_add_u64 v[192:193], s[42:43], 0, v[138:139]
	s_add_i32 m0, s37, 0x2000
	s_nop 0
	v_lshl_add_u64 v[192:193], v[252:253], 0, s[48:49]
	s_mov_b32 m0, s82
	s_nop 0
	s_mov_b32 m0, s83
	s_nop 0
	s_waitcnt vmcnt(0)
	s_waitcnt lgkmcnt(0)
	s_barrier
	s_setprio 1
	s_waitcnt lgkmcnt(0)
	v_mfma_f32_16x16x32_bf16 v[60:63], v[128:131], v[216:219], v[60:63]
	v_mfma_f32_16x16x32_bf16 v[56:59], v[170:173], v[216:219], v[56:59]
	v_mfma_f32_16x16x32_bf16 v[44:47], v[128:131], v[224:227], v[44:47]
	v_mfma_f32_16x16x32_bf16 v[40:43], v[170:173], v[224:227], v[40:43]
	v_mfma_f32_16x16x32_bf16 v[28:31], v[128:131], v[232:235], v[28:31]
	v_mfma_f32_16x16x32_bf16 v[24:27], v[170:173], v[232:235], v[24:27]
	v_mfma_f32_16x16x32_bf16 v[12:15], v[128:131], v[240:243], v[12:15]
	v_mfma_f32_16x16x32_bf16 v[8:11], v[170:173], v[240:243], v[8:11]
	v_mfma_f32_16x16x32_bf16 v[60:63], v[166:169], v[220:223], v[60:63]
	v_mfma_f32_16x16x32_bf16 v[56:59], v[174:177], v[220:223], v[56:59]
	v_mfma_f32_16x16x32_bf16 v[44:47], v[166:169], v[228:231], v[44:47]
	v_mfma_f32_16x16x32_bf16 v[40:43], v[174:177], v[228:231], v[40:43]
	v_mfma_f32_16x16x32_bf16 v[28:31], v[166:169], v[236:239], v[28:31]
	v_mfma_f32_16x16x32_bf16 v[24:27], v[174:177], v[236:239], v[24:27]
	v_mfma_f32_16x16x32_bf16 v[12:15], v[166:169], v[244:247], v[12:15]
	v_mfma_f32_16x16x32_bf16 v[8:11], v[174:177], v[244:247], v[8:11]
	s_setprio 0
	s_setprio 1
	v_mfma_f32_16x16x32_bf16 v[52:55], v[178:181], v[216:219], v[52:55]
	v_mfma_f32_16x16x32_bf16 v[48:51], v[208:211], v[216:219], v[48:51]
	v_mfma_f32_16x16x32_bf16 v[36:39], v[178:181], v[224:227], v[36:39]
	v_mfma_f32_16x16x32_bf16 v[32:35], v[208:211], v[224:227], v[32:35]
	v_mfma_f32_16x16x32_bf16 v[20:23], v[178:181], v[232:235], v[20:23]
	v_mfma_f32_16x16x32_bf16 v[16:19], v[208:211], v[232:235], v[16:19]
	v_mfma_f32_16x16x32_bf16 v[4:7], v[178:181], v[240:243], v[4:7]
	v_mfma_f32_16x16x32_bf16 v[0:3], v[208:211], v[240:243], v[0:3]
	v_mfma_f32_16x16x32_bf16 v[52:55], v[204:207], v[220:223], v[52:55]
	v_mfma_f32_16x16x32_bf16 v[48:51], v[212:215], v[220:223], v[48:51]
	v_mfma_f32_16x16x32_bf16 v[36:39], v[204:207], v[228:231], v[36:39]
	v_mfma_f32_16x16x32_bf16 v[32:35], v[212:215], v[228:231], v[32:35]
	v_mfma_f32_16x16x32_bf16 v[20:23], v[204:207], v[236:239], v[20:23]
	v_mfma_f32_16x16x32_bf16 v[16:19], v[212:215], v[236:239], v[16:19]
	v_mfma_f32_16x16x32_bf16 v[4:7], v[204:207], v[244:247], v[4:7]
	v_mfma_f32_16x16x32_bf16 v[0:3], v[212:215], v[244:247], v[0:3]
	s_setprio 0
	s_barrier
	s_add_i32 s36, s36, 2
	s_add_u32 s4, s4, 0x100
	s_addc_u32 s5, s5, 0
	s_add_u32 s30, s30, 0x100
	s_addc_u32 s31, s31, 0
	s_cmp_gt_u32 s36, 13
.Lpmi_after:
	s_and_b64 vcc, exec, s[20:21]
	s_cbranch_vccz .LBB0_597
	s_barrier

.LBB0_918:
	s_andn2_b64 vcc, exec, s[18:19]
	s_cbranch_vccnz .LBB0_585
	s_barrier
	s_branch .LBB0_585
.Ltramp_334:
	s_branch .LBB0_334

.LBB0_1161:
	s_mov_b32 s101, s4
	s_ashr_i32 s17, s16, 31
	s_lshl_b64 s[18:19], s[16:17], 19
	s_add_u32 s13, s27, s18
	s_addc_u32 s17, s30, s19
	s_ashr_i32 s15, s14, 31
	s_lshl_b64 s[20:21], s[14:15], 10
	s_add_u32 s18, s13, s20
	s_addc_u32 s19, s17, s21
	s_and_b64 s[56:57], s[4:5], exec
	s_cselect_b32 s15, s19, s55
	s_cselect_b32 s17, s18, s54
	s_ashr_i32 s13, s12, 31
	s_lshl_b64 s[56:57], s[12:13], 19
	s_add_u32 s13, s31, s56
	s_addc_u32 s25, s33, s57
	s_add_u32 s20, s13, s20
	s_addc_u32 s21, s25, s21
	s_and_b64 s[56:57], s[4:5], exec
	s_cselect_b32 s13, s21, s43
	s_cselect_b32 s25, s20, s42
	s_add_u32 s56, s54, 0x40080
	s_addc_u32 s57, s55, 0
	s_add_u32 s53, s42, 0x100
	v_mov_b32_e32 v0, 0
	s_addc_u32 s58, s43, 0
	s_mov_b32 s59, -2
	v_mov_b32_e32 v1, v0
	v_mov_b32_e32 v2, v0
	v_mov_b32_e32 v3, v0
	v_mov_b32_e32 v4, v0
	v_mov_b32_e32 v5, v0
	v_mov_b32_e32 v6, v0
	v_mov_b32_e32 v7, v0
	v_mov_b32_e32 v8, v0
	v_mov_b32_e32 v9, v0
	v_mov_b32_e32 v10, v0
	v_mov_b32_e32 v11, v0
	v_mov_b32_e32 v16, v0
	v_mov_b32_e32 v17, v0
	v_mov_b32_e32 v18, v0
	v_mov_b32_e32 v19, v0
	v_mov_b32_e32 v24, v0
	v_mov_b32_e32 v25, v0
	v_mov_b32_e32 v26, v0
	v_mov_b32_e32 v27, v0
	v_mov_b32_e32 v32, v0
	v_mov_b32_e32 v33, v0
	v_mov_b32_e32 v34, v0
	v_mov_b32_e32 v35, v0
	v_mov_b32_e32 v40, v0
	v_mov_b32_e32 v41, v0
	v_mov_b32_e32 v42, v0
	v_mov_b32_e32 v43, v0
	v_mov_b32_e32 v48, v0
	v_mov_b32_e32 v49, v0
	v_mov_b32_e32 v50, v0
	v_mov_b32_e32 v51, v0
	v_mov_b32_e32 v12, v0
	v_mov_b32_e32 v13, v0
	v_mov_b32_e32 v14, v0
	v_mov_b32_e32 v15, v0
	v_mov_b32_e32 v20, v0
	v_mov_b32_e32 v21, v0
	v_mov_b32_e32 v22, v0
	v_mov_b32_e32 v23, v0
	v_mov_b32_e32 v28, v0
	v_mov_b32_e32 v29, v0
	v_mov_b32_e32 v30, v0
	v_mov_b32_e32 v31, v0
	v_mov_b32_e32 v36, v0
	v_mov_b32_e32 v37, v0
	v_mov_b32_e32 v38, v0
	v_mov_b32_e32 v39, v0
	v_mov_b32_e32 v44, v0
	v_mov_b32_e32 v45, v0
	v_mov_b32_e32 v46, v0
	v_mov_b32_e32 v47, v0
	v_mov_b32_e32 v52, v0
	v_mov_b32_e32 v53, v0
	v_mov_b32_e32 v54, v0
	v_mov_b32_e32 v55, v0
	v_mov_b32_e32 v56, v0
	v_mov_b32_e32 v57, v0
	v_mov_b32_e32 v58, v0
	v_mov_b32_e32 v59, v0
	v_mov_b32_e32 v60, v0
	v_mov_b32_e32 v61, v0
	v_mov_b32_e32 v62, v0
	v_mov_b32_e32 v63, v0
	v_mov_b32_e32 v64, v0
	v_mov_b32_e32 v65, v0
	v_mov_b32_e32 v66, v0
	v_mov_b32_e32 v67, v0
	v_mov_b32_e32 v68, v0
	v_mov_b32_e32 v69, v0
	v_mov_b32_e32 v70, v0
	v_mov_b32_e32 v71, v0
	v_mov_b32_e32 v72, v0
	v_mov_b32_e32 v73, v0
	v_mov_b32_e32 v74, v0
	v_mov_b32_e32 v75, v0
	v_mov_b32_e32 v80, v0
	v_mov_b32_e32 v81, v0
	v_mov_b32_e32 v82, v0
	v_mov_b32_e32 v83, v0
	v_mov_b32_e32 v88, v0
	v_mov_b32_e32 v89, v0
	v_mov_b32_e32 v90, v0
	v_mov_b32_e32 v91, v0
	v_mov_b32_e32 v96, v0
	v_mov_b32_e32 v97, v0
	v_mov_b32_e32 v98, v0
	v_mov_b32_e32 v99, v0
	v_mov_b32_e32 v104, v0
	v_mov_b32_e32 v105, v0
	v_mov_b32_e32 v106, v0
	v_mov_b32_e32 v107, v0
	v_mov_b32_e32 v112, v0
	v_mov_b32_e32 v113, v0
	v_mov_b32_e32 v114, v0
	v_mov_b32_e32 v115, v0
	v_mov_b32_e32 v76, v0
	v_mov_b32_e32 v77, v0
	v_mov_b32_e32 v78, v0
	v_mov_b32_e32 v79, v0
	v_mov_b32_e32 v84, v0
	v_mov_b32_e32 v85, v0
	v_mov_b32_e32 v86, v0
	v_mov_b32_e32 v87, v0
	v_mov_b32_e32 v92, v0
	v_mov_b32_e32 v93, v0
	v_mov_b32_e32 v94, v0
	v_mov_b32_e32 v95, v0
	v_mov_b32_e32 v100, v0
	v_mov_b32_e32 v101, v0
	v_mov_b32_e32 v102, v0
	v_mov_b32_e32 v103, v0
	v_mov_b32_e32 v108, v0
	v_mov_b32_e32 v109, v0
	v_mov_b32_e32 v110, v0
	v_mov_b32_e32 v111, v0
	v_mov_b32_e32 v116, v0
	v_mov_b32_e32 v117, v0
	v_mov_b32_e32 v118, v0
	v_mov_b32_e32 v119, v0
	v_mov_b32_e32 v120, v0
	v_mov_b32_e32 v121, v0
	v_mov_b32_e32 v122, v0
	v_mov_b32_e32 v123, v0
	v_mov_b32_e32 v124, v0
	v_mov_b32_e32 v125, v0
	v_mov_b32_e32 v126, v0
	v_mov_b32_e32 v127, v0
.LBB0_1162:
	s_cmp_lg_u32 s59, 4
	s_cbranch_scc1 .Lpmo_body
	s_cmp_eq_u32 s101, 0
	s_cbranch_scc1 .Lpmo_tail
.Lpmo_body:
	s_add_u32 s42, s56, 0xfffc0080
	s_addc_u32 s43, s57, -1
	s_add_i32 s60, 0, 0x10000
	s_cmp_eq_u32 s59, 4
	s_cselect_b32 s55, s15, s43
	s_cselect_b32 s54, s17, s42
	v_add_u32_e32 v140, s60, v143
	s_cselect_b32 s43, s13, s58
	s_cselect_b32 s42, s25, s53
	s_add_i32 s62, 0, 0x14000
	ds_read_b128 v[156:159], v140
	ds_read_b128 v[160:163], v140 offset:1024
	ds_read_b128 v[164:167], v140 offset:2048
	ds_read_b128 v[168:171], v140 offset:3072
	v_add_u32_e32 v140, s62, v143
	ds_read_b128 v[172:175], v140
	ds_read_b128 v[176:179], v140 offset:1024
	ds_read_b128 v[204:207], v140 offset:2048
	ds_read_b128 v[208:211], v140 offset:3072
	v_lshl_add_u64 v[140:141], s[56:57], 0, v[136:137]
	s_add_i32 m0, s23, 0xc000
	ds_read_b128 v[212:215], v154
	ds_read_b128 v[216:219], v154 offset:1024
	ds_read_b128 v[220:223], v154 offset:2048
	ds_read_b128 v[224:227], v154 offset:3072
	ds_read_b128 v[228:231], v154 offset:4096
	ds_read_b128 v[232:235], v154 offset:5120
	ds_read_b128 v[236:239], v154 offset:6144
	ds_read_b128 v[240:243], v154 offset:7168
	global_load_lds_dwordx4 v[140:141], off
	v_lshl_add_u64 v[140:141], s[56:57], 0, v[138:139]
	s_add_i32 m0, s23, 0xe000
	s_nop 0
	global_load_lds_dwordx4 v[140:141], off
	s_waitcnt vmcnt(8)
	s_waitcnt lgkmcnt(0)
	s_barrier
	s_setprio 1
	s_waitcnt lgkmcnt(0)
	v_mfma_f32_16x16x32_bf16 v[124:127], v[156:159], v[212:215], v[124:127]
	v_mfma_f32_16x16x32_bf16 v[120:123], v[164:167], v[212:215], v[120:123]
	v_mfma_f32_16x16x32_bf16 v[116:119], v[156:159], v[220:223], v[116:119]
	v_mfma_f32_16x16x32_bf16 v[108:111], v[164:167], v[220:223], v[108:111]
	v_mfma_f32_16x16x32_bf16 v[100:103], v[156:159], v[228:231], v[100:103]
	v_mfma_f32_16x16x32_bf16 v[92:95], v[164:167], v[228:231], v[92:95]
	v_mfma_f32_16x16x32_bf16 v[84:87], v[156:159], v[236:239], v[84:87]
	v_mfma_f32_16x16x32_bf16 v[76:79], v[164:167], v[236:239], v[76:79]
	v_mfma_f32_16x16x32_bf16 v[124:127], v[160:163], v[216:219], v[124:127]
	v_mfma_f32_16x16x32_bf16 v[120:123], v[168:171], v[216:219], v[120:123]
	v_mfma_f32_16x16x32_bf16 v[116:119], v[160:163], v[224:227], v[116:119]
	v_mfma_f32_16x16x32_bf16 v[108:111], v[168:171], v[224:227], v[108:111]
	v_mfma_f32_16x16x32_bf16 v[100:103], v[160:163], v[232:235], v[100:103]
	v_mfma_f32_16x16x32_bf16 v[92:95], v[168:171], v[232:235], v[92:95]
	v_mfma_f32_16x16x32_bf16 v[84:87], v[160:163], v[240:243], v[84:87]
	v_mfma_f32_16x16x32_bf16 v[76:79], v[168:171], v[240:243], v[76:79]
	s_setprio 0
	s_setprio 1
	v_mfma_f32_16x16x32_bf16 v[112:115], v[172:175], v[212:215], v[112:115]
	v_mfma_f32_16x16x32_bf16 v[104:107], v[204:207], v[212:215], v[104:107]
	v_mfma_f32_16x16x32_bf16 v[96:99], v[172:175], v[220:223], v[96:99]
	v_mfma_f32_16x16x32_bf16 v[88:91], v[204:207], v[220:223], v[88:91]
	v_mfma_f32_16x16x32_bf16 v[80:83], v[172:175], v[228:231], v[80:83]
	v_mfma_f32_16x16x32_bf16 v[72:75], v[204:207], v[228:231], v[72:75]
	v_mfma_f32_16x16x32_bf16 v[68:71], v[172:175], v[236:239], v[68:71]
	v_mfma_f32_16x16x32_bf16 v[64:67], v[204:207], v[236:239], v[64:67]
	v_mfma_f32_16x16x32_bf16 v[112:115], v[176:179], v[216:219], v[112:115]
	v_mfma_f32_16x16x32_bf16 v[104:107], v[208:211], v[216:219], v[104:107]
	v_mfma_f32_16x16x32_bf16 v[96:99], v[176:179], v[224:227], v[96:99]
	v_mfma_f32_16x16x32_bf16 v[88:91], v[208:211], v[224:227], v[88:91]
	v_mfma_f32_16x16x32_bf16 v[80:83], v[176:179], v[232:235], v[80:83]
	v_mfma_f32_16x16x32_bf16 v[72:75], v[208:211], v[232:235], v[72:75]
	v_mfma_f32_16x16x32_bf16 v[68:71], v[176:179], v[240:243], v[68:71]
	v_mfma_f32_16x16x32_bf16 v[64:67], v[208:211], v[240:243], v[64:67]
	s_setprio 0
	s_barrier
	s_add_i32 s60, s60, s36
	v_lshl_add_u64 v[140:141], s[42:43], 0, v[130:131]
	s_mov_b32 m0, s60
	ds_read_b128 v[212:215], v154 offset:16384
	ds_read_b128 v[216:219], v154 offset:17408
	ds_read_b128 v[220:223], v154 offset:18432
	ds_read_b128 v[224:227], v154 offset:19456
	ds_read_b128 v[228:231], v154 offset:20480
	ds_read_b128 v[232:235], v154 offset:21504
	ds_read_b128 v[236:239], v154 offset:22528
	ds_read_b128 v[240:243], v154 offset:23552
	global_load_lds_dwordx4 v[140:141], off
	s_add_i32 m0, s60, 0x2000
	s_add_u32 s60, s42, 0x40000
	v_lshl_add_u64 v[180:181], s[42:43], 0, v[134:135]
	s_addc_u32 s61, s43, 0
	s_add_i32 s62, s62, s36
	global_load_lds_dwordx4 v[180:181], off
	v_lshl_add_u64 v[190:191], s[60:61], 0, v[130:131]
	s_mov_b32 m0, s62
	v_lshl_add_u64 v[192:193], s[54:55], 0, v[132:133]
	global_load_lds_dwordx4 v[190:191], off
	v_lshl_add_u64 v[190:191], s[60:61], 0, v[134:135]
	s_add_i32 m0, s62, 0x2000
	s_nop 0
	global_load_lds_dwordx4 v[190:191], off
	v_lshl_add_u64 v[190:191], s[54:55], 0, v[128:129]
	s_mov_b32 m0, s23
	s_nop 0
	global_load_lds_dwordx4 v[190:191], off
	s_mov_b32 m0, s37
	s_nop 0
	global_load_lds_dwordx4 v[192:193], off
	s_waitcnt vmcnt(8)
	s_waitcnt lgkmcnt(0)
	s_barrier
	s_setprio 1
	s_waitcnt lgkmcnt(0)
	v_mfma_f32_16x16x32_bf16 v[60:63], v[156:159], v[212:215], v[60:63]
	v_mfma_f32_16x16x32_bf16 v[56:59], v[164:167], v[212:215], v[56:59]
	v_mfma_f32_16x16x32_bf16 v[52:55], v[156:159], v[220:223], v[52:55]
	v_mfma_f32_16x16x32_bf16 v[44:47], v[164:167], v[220:223], v[44:47]
	v_mfma_f32_16x16x32_bf16 v[36:39], v[156:159], v[228:231], v[36:39]
	v_mfma_f32_16x16x32_bf16 v[28:31], v[164:167], v[228:231], v[28:31]
	v_mfma_f32_16x16x32_bf16 v[20:23], v[156:159], v[236:239], v[20:23]
	v_mfma_f32_16x16x32_bf16 v[12:15], v[164:167], v[236:239], v[12:15]
	v_mfma_f32_16x16x32_bf16 v[60:63], v[160:163], v[216:219], v[60:63]
	v_mfma_f32_16x16x32_bf16 v[56:59], v[168:171], v[216:219], v[56:59]
	v_mfma_f32_16x16x32_bf16 v[52:55], v[160:163], v[224:227], v[52:55]
	v_mfma_f32_16x16x32_bf16 v[44:47], v[168:171], v[224:227], v[44:47]
	v_mfma_f32_16x16x32_bf16 v[36:39], v[160:163], v[232:235], v[36:39]
	v_mfma_f32_16x16x32_bf16 v[28:31], v[168:171], v[232:235], v[28:31]
	v_mfma_f32_16x16x32_bf16 v[20:23], v[160:163], v[240:243], v[20:23]
	v_mfma_f32_16x16x32_bf16 v[12:15], v[168:171], v[240:243], v[12:15]
	s_setprio 0
	s_setprio 1
	v_mfma_f32_16x16x32_bf16 v[48:51], v[172:175], v[212:215], v[48:51]
	v_mfma_f32_16x16x32_bf16 v[40:43], v[204:207], v[212:215], v[40:43]
	v_mfma_f32_16x16x32_bf16 v[32:35], v[172:175], v[220:223], v[32:35]
	v_mfma_f32_16x16x32_bf16 v[24:27], v[204:207], v[220:223], v[24:27]
	v_mfma_f32_16x16x32_bf16 v[16:19], v[172:175], v[228:231], v[16:19]
	v_mfma_f32_16x16x32_bf16 v[8:11], v[204:207], v[228:231], v[8:11]
	v_mfma_f32_16x16x32_bf16 v[4:7], v[172:175], v[236:239], v[4:7]
	v_mfma_f32_16x16x32_bf16 v[0:3], v[204:207], v[236:239], v[0:3]
	v_mfma_f32_16x16x32_bf16 v[48:51], v[176:179], v[216:219], v[48:51]
	v_mfma_f32_16x16x32_bf16 v[40:43], v[208:211], v[216:219], v[40:43]
	v_mfma_f32_16x16x32_bf16 v[32:35], v[176:179], v[224:227], v[32:35]
	v_mfma_f32_16x16x32_bf16 v[24:27], v[208:211], v[224:227], v[24:27]
	v_mfma_f32_16x16x32_bf16 v[16:19], v[176:179], v[232:235], v[16:19]
	v_mfma_f32_16x16x32_bf16 v[8:11], v[208:211], v[232:235], v[8:11]
	v_mfma_f32_16x16x32_bf16 v[4:7], v[176:179], v[240:243], v[4:7]
	v_mfma_f32_16x16x32_bf16 v[0:3], v[208:211], v[240:243], v[0:3]
	s_setprio 0
	s_barrier
	s_add_i32 s60, 0, 0x18000
	v_add_u32_e32 v155, s60, v143
	s_add_i32 s61, 0, 0x1c000
	ds_read_b128 v[156:159], v155
	ds_read_b128 v[160:163], v155 offset:1024
	ds_read_b128 v[164:167], v155 offset:2048
	ds_read_b128 v[168:171], v155 offset:3072
	v_add_u32_e32 v155, s61, v143
	ds_read_b128 v[172:175], v155
	ds_read_b128 v[176:179], v155 offset:1024
	ds_read_b128 v[204:207], v155 offset:2048
	ds_read_b128 v[208:211], v155 offset:3072
	s_add_u32 s54, s54, 0x40000
	s_addc_u32 s55, s55, 0
	s_mov_b32 m0, s40
	v_lshl_add_u64 v[244:245], s[54:55], 0, v[128:129]
	ds_read_b128 v[212:215], v154 offset:32768
	ds_read_b128 v[216:219], v154 offset:33792
	ds_read_b128 v[220:223], v154 offset:34816
	ds_read_b128 v[224:227], v154 offset:35840
	ds_read_b128 v[228:231], v154 offset:36864
	ds_read_b128 v[232:235], v154 offset:37888
	ds_read_b128 v[236:239], v154 offset:38912
	ds_read_b128 v[240:243], v154 offset:39936
	global_load_lds_dwordx4 v[244:245], off
	v_lshl_add_u64 v[244:245], s[54:55], 0, v[132:133]
	s_mov_b32 m0, s41
	s_nop 0
	global_load_lds_dwordx4 v[244:245], off
	s_waitcnt vmcnt(8)
	s_waitcnt lgkmcnt(0)
	s_barrier
	s_setprio 1
	s_waitcnt lgkmcnt(0)
	v_mfma_f32_16x16x32_bf16 v[124:127], v[156:159], v[212:215], v[124:127]
	v_mfma_f32_16x16x32_bf16 v[120:123], v[164:167], v[212:215], v[120:123]
	v_mfma_f32_16x16x32_bf16 v[116:119], v[156:159], v[220:223], v[116:119]
	v_mfma_f32_16x16x32_bf16 v[108:111], v[164:167], v[220:223], v[108:111]
	v_mfma_f32_16x16x32_bf16 v[100:103], v[156:159], v[228:231], v[100:103]
	v_mfma_f32_16x16x32_bf16 v[92:95], v[164:167], v[228:231], v[92:95]
	v_mfma_f32_16x16x32_bf16 v[84:87], v[156:159], v[236:239], v[84:87]
	v_mfma_f32_16x16x32_bf16 v[76:79], v[164:167], v[236:239], v[76:79]
	v_mfma_f32_16x16x32_bf16 v[124:127], v[160:163], v[216:219], v[124:127]
	v_mfma_f32_16x16x32_bf16 v[120:123], v[168:171], v[216:219], v[120:123]
	v_mfma_f32_16x16x32_bf16 v[116:119], v[160:163], v[224:227], v[116:119]
	v_mfma_f32_16x16x32_bf16 v[108:111], v[168:171], v[224:227], v[108:111]
	v_mfma_f32_16x16x32_bf16 v[100:103], v[160:163], v[232:235], v[100:103]
	v_mfma_f32_16x16x32_bf16 v[92:95], v[168:171], v[232:235], v[92:95]
	v_mfma_f32_16x16x32_bf16 v[84:87], v[160:163], v[240:243], v[84:87]
	v_mfma_f32_16x16x32_bf16 v[76:79], v[168:171], v[240:243], v[76:79]
	s_setprio 0
	s_setprio 1
	v_mfma_f32_16x16x32_bf16 v[112:115], v[172:175], v[212:215], v[112:115]
	v_mfma_f32_16x16x32_bf16 v[104:107], v[204:207], v[212:215], v[104:107]
	v_mfma_f32_16x16x32_bf16 v[96:99], v[172:175], v[220:223], v[96:99]
	v_mfma_f32_16x16x32_bf16 v[88:91], v[204:207], v[220:223], v[88:91]
	v_mfma_f32_16x16x32_bf16 v[80:83], v[172:175], v[228:231], v[80:83]
	v_mfma_f32_16x16x32_bf16 v[72:75], v[204:207], v[228:231], v[72:75]
	v_mfma_f32_16x16x32_bf16 v[68:71], v[172:175], v[236:239], v[68:71]
	v_mfma_f32_16x16x32_bf16 v[64:67], v[204:207], v[236:239], v[64:67]
	v_mfma_f32_16x16x32_bf16 v[112:115], v[176:179], v[216:219], v[112:115]
	v_mfma_f32_16x16x32_bf16 v[104:107], v[208:211], v[216:219], v[104:107]
	v_mfma_f32_16x16x32_bf16 v[96:99], v[176:179], v[224:227], v[96:99]
	v_mfma_f32_16x16x32_bf16 v[88:91], v[208:211], v[224:227], v[88:91]
	v_mfma_f32_16x16x32_bf16 v[80:83], v[176:179], v[232:235], v[80:83]
	v_mfma_f32_16x16x32_bf16 v[72:75], v[208:211], v[232:235], v[72:75]
	v_mfma_f32_16x16x32_bf16 v[68:71], v[176:179], v[240:243], v[68:71]
	v_mfma_f32_16x16x32_bf16 v[64:67], v[208:211], v[240:243], v[64:67]
	s_setprio 0
	s_barrier
	s_add_i32 s54, s60, s36
	v_lshl_add_u64 v[140:141], v[140:141], 0, s[48:49]
	s_mov_b32 m0, s54
	ds_read_b128 v[212:215], v154 offset:49152
	ds_read_b128 v[216:219], v154 offset:50176
	ds_read_b128 v[220:223], v154 offset:51200
	ds_read_b128 v[224:227], v154 offset:52224
	ds_read_b128 v[228:231], v154 offset:53248
	ds_read_b128 v[232:235], v154 offset:54272
	ds_read_b128 v[236:239], v154 offset:55296
	ds_read_b128 v[240:243], v154 offset:56320
	global_load_lds_dwordx4 v[140:141], off
	s_add_i32 m0, s54, 0x2000
	s_add_u32 s42, s42, 0x40080
	v_lshl_add_u64 v[140:141], v[180:181], 0, s[48:49]
	s_addc_u32 s43, s43, 0
	s_add_i32 s54, s61, s36
	global_load_lds_dwordx4 v[140:141], off
	v_lshl_add_u64 v[140:141], s[42:43], 0, v[130:131]
	s_mov_b32 m0, s54
	s_nop 0
	global_load_lds_dwordx4 v[140:141], off
	v_lshl_add_u64 v[140:141], s[42:43], 0, v[134:135]
	s_add_i32 m0, s54, 0x2000
	s_nop 0
	global_load_lds_dwordx4 v[140:141], off
	v_lshl_add_u64 v[140:141], v[190:191], 0, s[48:49]
	s_mov_b32 m0, s44
	s_nop 0
	global_load_lds_dwordx4 v[140:141], off
	v_lshl_add_u64 v[140:141], v[192:193], 0, s[48:49]
	s_mov_b32 m0, s45
	s_nop 0
	global_load_lds_dwordx4 v[140:141], off
	s_waitcnt vmcnt(8)
	s_waitcnt lgkmcnt(0)
	s_barrier
	s_setprio 1
	s_waitcnt lgkmcnt(0)
	v_mfma_f32_16x16x32_bf16 v[60:63], v[156:159], v[212:215], v[60:63]
	v_mfma_f32_16x16x32_bf16 v[56:59], v[164:167], v[212:215], v[56:59]
	v_mfma_f32_16x16x32_bf16 v[52:55], v[156:159], v[220:223], v[52:55]
	v_mfma_f32_16x16x32_bf16 v[44:47], v[164:167], v[220:223], v[44:47]
	v_mfma_f32_16x16x32_bf16 v[36:39], v[156:159], v[228:231], v[36:39]
	v_mfma_f32_16x16x32_bf16 v[28:31], v[164:167], v[228:231], v[28:31]
	v_mfma_f32_16x16x32_bf16 v[20:23], v[156:159], v[236:239], v[20:23]
	v_mfma_f32_16x16x32_bf16 v[12:15], v[164:167], v[236:239], v[12:15]
	v_mfma_f32_16x16x32_bf16 v[60:63], v[160:163], v[216:219], v[60:63]
	v_mfma_f32_16x16x32_bf16 v[56:59], v[168:171], v[216:219], v[56:59]
	v_mfma_f32_16x16x32_bf16 v[52:55], v[160:163], v[224:227], v[52:55]
	v_mfma_f32_16x16x32_bf16 v[44:47], v[168:171], v[224:227], v[44:47]
	v_mfma_f32_16x16x32_bf16 v[36:39], v[160:163], v[232:235], v[36:39]
	v_mfma_f32_16x16x32_bf16 v[28:31], v[168:171], v[232:235], v[28:31]
	v_mfma_f32_16x16x32_bf16 v[20:23], v[160:163], v[240:243], v[20:23]
	v_mfma_f32_16x16x32_bf16 v[12:15], v[168:171], v[240:243], v[12:15]
	s_setprio 0
	s_setprio 1
	v_mfma_f32_16x16x32_bf16 v[48:51], v[172:175], v[212:215], v[48:51]
	v_mfma_f32_16x16x32_bf16 v[40:43], v[204:207], v[212:215], v[40:43]
	v_mfma_f32_16x16x32_bf16 v[32:35], v[172:175], v[220:223], v[32:35]
	v_mfma_f32_16x16x32_bf16 v[24:27], v[204:207], v[220:223], v[24:27]
	v_mfma_f32_16x16x32_bf16 v[16:19], v[172:175], v[228:231], v[16:19]
	v_mfma_f32_16x16x32_bf16 v[8:11], v[204:207], v[228:231], v[8:11]
	v_mfma_f32_16x16x32_bf16 v[4:7], v[172:175], v[236:239], v[4:7]
	v_mfma_f32_16x16x32_bf16 v[0:3], v[204:207], v[236:239], v[0:3]
	v_mfma_f32_16x16x32_bf16 v[48:51], v[176:179], v[216:219], v[48:51]
	v_mfma_f32_16x16x32_bf16 v[40:43], v[208:211], v[216:219], v[40:43]
	v_mfma_f32_16x16x32_bf16 v[32:35], v[176:179], v[224:227], v[32:35]
	v_mfma_f32_16x16x32_bf16 v[24:27], v[208:211], v[224:227], v[24:27]
	v_mfma_f32_16x16x32_bf16 v[16:19], v[176:179], v[232:235], v[16:19]
	v_mfma_f32_16x16x32_bf16 v[8:11], v[208:211], v[232:235], v[8:11]
	v_mfma_f32_16x16x32_bf16 v[4:7], v[176:179], v[240:243], v[4:7]
	v_mfma_f32_16x16x32_bf16 v[0:3], v[208:211], v[240:243], v[0:3]
	s_setprio 0
	s_barrier
	s_add_i32 s59, s59, 2
	s_add_u32 s56, s56, 0x100
	s_addc_u32 s57, s57, 0
	s_add_u32 s53, s53, 0x100
	s_addc_u32 s58, s58, 0
	s_cmp_gt_u32 s59, 5
	s_cbranch_scc0 .LBB0_1162
	s_branch .Lpmo_after
.Lpmo_tail:
	s_add_u32 s42, s56, 0xfffc0080
	s_addc_u32 s43, s57, -1
	s_add_i32 s60, 0, 0x10000
	s_cmp_eq_u32 s59, 4
	s_cselect_b32 s55, s15, s43
	s_cselect_b32 s54, s17, s42
	v_add_u32_e32 v140, s60, v143
	s_cselect_b32 s43, s13, s58
	s_cselect_b32 s42, s25, s53
	s_add_i32 s62, 0, 0x14000
	ds_read_b128 v[156:159], v140
	ds_read_b128 v[160:163], v140 offset:1024
	ds_read_b128 v[164:167], v140 offset:2048
	ds_read_b128 v[168:171], v140 offset:3072
	v_add_u32_e32 v140, s62, v143
	ds_read_b128 v[172:175], v140
	ds_read_b128 v[176:179], v140 offset:1024
	ds_read_b128 v[204:207], v140 offset:2048
	ds_read_b128 v[208:211], v140 offset:3072
	v_lshl_add_u64 v[140:141], s[56:57], 0, v[136:137]
	s_add_i32 m0, s23, 0xc000
	ds_read_b128 v[212:215], v154
	ds_read_b128 v[216:219], v154 offset:1024
	ds_read_b128 v[220:223], v154 offset:2048
	ds_read_b128 v[224:227], v154 offset:3072
	ds_read_b128 v[228:231], v154 offset:4096
	ds_read_b128 v[232:235], v154 offset:5120
	ds_read_b128 v[236:239], v154 offset:6144
	ds_read_b128 v[240:243], v154 offset:7168
	global_load_lds_dwordx4 v[140:141], off
	v_lshl_add_u64 v[140:141], s[56:57], 0, v[138:139]
	s_add_i32 m0, s23, 0xe000
	s_nop 0
	global_load_lds_dwordx4 v[140:141], off
	s_waitcnt vmcnt(8)
	s_waitcnt lgkmcnt(0)
	s_barrier
	s_setprio 1
	s_waitcnt lgkmcnt(0)
	v_mfma_f32_16x16x32_bf16 v[124:127], v[156:159], v[212:215], v[124:127]
	v_mfma_f32_16x16x32_bf16 v[120:123], v[164:167], v[212:215], v[120:123]
	v_mfma_f32_16x16x32_bf16 v[116:119], v[156:159], v[220:223], v[116:119]
	v_mfma_f32_16x16x32_bf16 v[108:111], v[164:167], v[220:223], v[108:111]
	v_mfma_f32_16x16x32_bf16 v[100:103], v[156:159], v[228:231], v[100:103]
	v_mfma_f32_16x16x32_bf16 v[92:95], v[164:167], v[228:231], v[92:95]
	v_mfma_f32_16x16x32_bf16 v[84:87], v[156:159], v[236:239], v[84:87]
	v_mfma_f32_16x16x32_bf16 v[76:79], v[164:167], v[236:239], v[76:79]
	v_mfma_f32_16x16x32_bf16 v[124:127], v[160:163], v[216:219], v[124:127]
	v_mfma_f32_16x16x32_bf16 v[120:123], v[168:171], v[216:219], v[120:123]
	v_mfma_f32_16x16x32_bf16 v[116:119], v[160:163], v[224:227], v[116:119]
	v_mfma_f32_16x16x32_bf16 v[108:111], v[168:171], v[224:227], v[108:111]
	v_mfma_f32_16x16x32_bf16 v[100:103], v[160:163], v[232:235], v[100:103]
	v_mfma_f32_16x16x32_bf16 v[92:95], v[168:171], v[232:235], v[92:95]
	v_mfma_f32_16x16x32_bf16 v[84:87], v[160:163], v[240:243], v[84:87]
	v_mfma_f32_16x16x32_bf16 v[76:79], v[168:171], v[240:243], v[76:79]
	s_setprio 0
	s_setprio 1
	v_mfma_f32_16x16x32_bf16 v[112:115], v[172:175], v[212:215], v[112:115]
	v_mfma_f32_16x16x32_bf16 v[104:107], v[204:207], v[212:215], v[104:107]
	v_mfma_f32_16x16x32_bf16 v[96:99], v[172:175], v[220:223], v[96:99]
	v_mfma_f32_16x16x32_bf16 v[88:91], v[204:207], v[220:223], v[88:91]
	v_mfma_f32_16x16x32_bf16 v[80:83], v[172:175], v[228:231], v[80:83]
	v_mfma_f32_16x16x32_bf16 v[72:75], v[204:207], v[228:231], v[72:75]
	v_mfma_f32_16x16x32_bf16 v[68:71], v[172:175], v[236:239], v[68:71]
	v_mfma_f32_16x16x32_bf16 v[64:67], v[204:207], v[236:239], v[64:67]
	v_mfma_f32_16x16x32_bf16 v[112:115], v[176:179], v[216:219], v[112:115]
	v_mfma_f32_16x16x32_bf16 v[104:107], v[208:211], v[216:219], v[104:107]
	v_mfma_f32_16x16x32_bf16 v[96:99], v[176:179], v[224:227], v[96:99]
	v_mfma_f32_16x16x32_bf16 v[88:91], v[208:211], v[224:227], v[88:91]
	v_mfma_f32_16x16x32_bf16 v[80:83], v[176:179], v[232:235], v[80:83]
	v_mfma_f32_16x16x32_bf16 v[72:75], v[208:211], v[232:235], v[72:75]
	v_mfma_f32_16x16x32_bf16 v[68:71], v[176:179], v[240:243], v[68:71]
	v_mfma_f32_16x16x32_bf16 v[64:67], v[208:211], v[240:243], v[64:67]
	s_setprio 0
	s_barrier
	s_add_i32 s60, s60, s36
	v_lshl_add_u64 v[140:141], s[42:43], 0, v[130:131]
	s_mov_b32 m0, s60
	ds_read_b128 v[212:215], v154 offset:16384
	ds_read_b128 v[216:219], v154 offset:17408
	ds_read_b128 v[220:223], v154 offset:18432
	ds_read_b128 v[224:227], v154 offset:19456
	ds_read_b128 v[228:231], v154 offset:20480
	ds_read_b128 v[232:235], v154 offset:21504
	ds_read_b128 v[236:239], v154 offset:22528
	ds_read_b128 v[240:243], v154 offset:23552
	s_add_i32 m0, s60, 0x2000
	s_add_u32 s60, s42, 0x40000
	v_lshl_add_u64 v[180:181], s[42:43], 0, v[134:135]
	s_addc_u32 s61, s43, 0
	s_add_i32 s62, s62, s36
	v_lshl_add_u64 v[190:191], s[60:61], 0, v[130:131]
	s_mov_b32 m0, s62
	v_lshl_add_u64 v[192:193], s[54:55], 0, v[132:133]
	v_lshl_add_u64 v[190:191], s[60:61], 0, v[134:135]
	s_add_i32 m0, s62, 0x2000
	s_nop 0
	v_lshl_add_u64 v[190:191], s[54:55], 0, v[128:129]
	s_mov_b32 m0, s23
	s_nop 0
	s_mov_b32 m0, s37
	s_nop 0
	s_waitcnt vmcnt(2)
	s_waitcnt lgkmcnt(0)
	s_barrier
	s_setprio 1
	s_waitcnt lgkmcnt(0)
	v_mfma_f32_16x16x32_bf16 v[60:63], v[156:159], v[212:215], v[60:63]
	v_mfma_f32_16x16x32_bf16 v[56:59], v[164:167], v[212:215], v[56:59]
	v_mfma_f32_16x16x32_bf16 v[52:55], v[156:159], v[220:223], v[52:55]
	v_mfma_f32_16x16x32_bf16 v[44:47], v[164:167], v[220:223], v[44:47]
	v_mfma_f32_16x16x32_bf16 v[36:39], v[156:159], v[228:231], v[36:39]
	v_mfma_f32_16x16x32_bf16 v[28:31], v[164:167], v[228:231], v[28:31]
	v_mfma_f32_16x16x32_bf16 v[20:23], v[156:159], v[236:239], v[20:23]
	v_mfma_f32_16x16x32_bf16 v[12:15], v[164:167], v[236:239], v[12:15]
	v_mfma_f32_16x16x32_bf16 v[60:63], v[160:163], v[216:219], v[60:63]
	v_mfma_f32_16x16x32_bf16 v[56:59], v[168:171], v[216:219], v[56:59]
	v_mfma_f32_16x16x32_bf16 v[52:55], v[160:163], v[224:227], v[52:55]
	v_mfma_f32_16x16x32_bf16 v[44:47], v[168:171], v[224:227], v[44:47]
	v_mfma_f32_16x16x32_bf16 v[36:39], v[160:163], v[232:235], v[36:39]
	v_mfma_f32_16x16x32_bf16 v[28:31], v[168:171], v[232:235], v[28:31]
	v_mfma_f32_16x16x32_bf16 v[20:23], v[160:163], v[240:243], v[20:23]
	v_mfma_f32_16x16x32_bf16 v[12:15], v[168:171], v[240:243], v[12:15]
	s_setprio 0
	s_setprio 1
	v_mfma_f32_16x16x32_bf16 v[48:51], v[172:175], v[212:215], v[48:51]
	v_mfma_f32_16x16x32_bf16 v[40:43], v[204:207], v[212:215], v[40:43]
	v_mfma_f32_16x16x32_bf16 v[32:35], v[172:175], v[220:223], v[32:35]
	v_mfma_f32_16x16x32_bf16 v[24:27], v[204:207], v[220:223], v[24:27]
	v_mfma_f32_16x16x32_bf16 v[16:19], v[172:175], v[228:231], v[16:19]
	v_mfma_f32_16x16x32_bf16 v[8:11], v[204:207], v[228:231], v[8:11]
	v_mfma_f32_16x16x32_bf16 v[4:7], v[172:175], v[236:239], v[4:7]
	v_mfma_f32_16x16x32_bf16 v[0:3], v[204:207], v[236:239], v[0:3]
	v_mfma_f32_16x16x32_bf16 v[48:51], v[176:179], v[216:219], v[48:51]
	v_mfma_f32_16x16x32_bf16 v[40:43], v[208:211], v[216:219], v[40:43]
	v_mfma_f32_16x16x32_bf16 v[32:35], v[176:179], v[224:227], v[32:35]
	v_mfma_f32_16x16x32_bf16 v[24:27], v[208:211], v[224:227], v[24:27]
	v_mfma_f32_16x16x32_bf16 v[16:19], v[176:179], v[232:235], v[16:19]
	v_mfma_f32_16x16x32_bf16 v[8:11], v[208:211], v[232:235], v[8:11]
	v_mfma_f32_16x16x32_bf16 v[4:7], v[176:179], v[240:243], v[4:7]
	v_mfma_f32_16x16x32_bf16 v[0:3], v[208:211], v[240:243], v[0:3]
	s_setprio 0
	s_barrier
	s_add_i32 s60, 0, 0x18000
	v_add_u32_e32 v155, s60, v143
	s_add_i32 s61, 0, 0x1c000
	ds_read_b128 v[156:159], v155
	ds_read_b128 v[160:163], v155 offset:1024
	ds_read_b128 v[164:167], v155 offset:2048
	ds_read_b128 v[168:171], v155 offset:3072
	v_add_u32_e32 v155, s61, v143
	ds_read_b128 v[172:175], v155
	ds_read_b128 v[176:179], v155 offset:1024
	ds_read_b128 v[204:207], v155 offset:2048
	ds_read_b128 v[208:211], v155 offset:3072
	s_add_u32 s54, s54, 0x40000
	s_addc_u32 s55, s55, 0
	s_mov_b32 m0, s40
	v_lshl_add_u64 v[244:245], s[54:55], 0, v[128:129]
	ds_read_b128 v[212:215], v154 offset:32768
	ds_read_b128 v[216:219], v154 offset:33792
	ds_read_b128 v[220:223], v154 offset:34816
	ds_read_b128 v[224:227], v154 offset:35840
	ds_read_b128 v[228:231], v154 offset:36864
	ds_read_b128 v[232:235], v154 offset:37888
	ds_read_b128 v[236:239], v154 offset:38912
	ds_read_b128 v[240:243], v154 offset:39936
	v_lshl_add_u64 v[244:245], s[54:55], 0, v[132:133]
	s_mov_b32 m0, s41
	s_nop 0
	s_waitcnt vmcnt(0)
	s_waitcnt lgkmcnt(0)
	s_barrier
	s_setprio 1
	s_waitcnt lgkmcnt(0)
	v_mfma_f32_16x16x32_bf16 v[124:127], v[156:159], v[212:215], v[124:127]
	v_mfma_f32_16x16x32_bf16 v[120:123], v[164:167], v[212:215], v[120:123]
	v_mfma_f32_16x16x32_bf16 v[116:119], v[156:159], v[220:223], v[116:119]
	v_mfma_f32_16x16x32_bf16 v[108:111], v[164:167], v[220:223], v[108:111]
	v_mfma_f32_16x16x32_bf16 v[100:103], v[156:159], v[228:231], v[100:103]
	v_mfma_f32_16x16x32_bf16 v[92:95], v[164:167], v[228:231], v[92:95]
	v_mfma_f32_16x16x32_bf16 v[84:87], v[156:159], v[236:239], v[84:87]
	v_mfma_f32_16x16x32_bf16 v[76:79], v[164:167], v[236:239], v[76:79]
	v_mfma_f32_16x16x32_bf16 v[124:127], v[160:163], v[216:219], v[124:127]
	v_mfma_f32_16x16x32_bf16 v[120:123], v[168:171], v[216:219], v[120:123]
	v_mfma_f32_16x16x32_bf16 v[116:119], v[160:163], v[224:227], v[116:119]
	v_mfma_f32_16x16x32_bf16 v[108:111], v[168:171], v[224:227], v[108:111]
	v_mfma_f32_16x16x32_bf16 v[100:103], v[160:163], v[232:235], v[100:103]
	v_mfma_f32_16x16x32_bf16 v[92:95], v[168:171], v[232:235], v[92:95]
	v_mfma_f32_16x16x32_bf16 v[84:87], v[160:163], v[240:243], v[84:87]
	v_mfma_f32_16x16x32_bf16 v[76:79], v[168:171], v[240:243], v[76:79]
	s_setprio 0
	s_setprio 1
	v_mfma_f32_16x16x32_bf16 v[112:115], v[172:175], v[212:215], v[112:115]
	v_mfma_f32_16x16x32_bf16 v[104:107], v[204:207], v[212:215], v[104:107]
	v_mfma_f32_16x16x32_bf16 v[96:99], v[172:175], v[220:223], v[96:99]
	v_mfma_f32_16x16x32_bf16 v[88:91], v[204:207], v[220:223], v[88:91]
	v_mfma_f32_16x16x32_bf16 v[80:83], v[172:175], v[228:231], v[80:83]
	v_mfma_f32_16x16x32_bf16 v[72:75], v[204:207], v[228:231], v[72:75]
	v_mfma_f32_16x16x32_bf16 v[68:71], v[172:175], v[236:239], v[68:71]
	v_mfma_f32_16x16x32_bf16 v[64:67], v[204:207], v[236:239], v[64:67]
	v_mfma_f32_16x16x32_bf16 v[112:115], v[176:179], v[216:219], v[112:115]
	v_mfma_f32_16x16x32_bf16 v[104:107], v[208:211], v[216:219], v[104:107]
	v_mfma_f32_16x16x32_bf16 v[96:99], v[176:179], v[224:227], v[96:99]
	v_mfma_f32_16x16x32_bf16 v[88:91], v[208:211], v[224:227], v[88:91]
	v_mfma_f32_16x16x32_bf16 v[80:83], v[176:179], v[232:235], v[80:83]
	v_mfma_f32_16x16x32_bf16 v[72:75], v[208:211], v[232:235], v[72:75]
	v_mfma_f32_16x16x32_bf16 v[68:71], v[176:179], v[240:243], v[68:71]
	v_mfma_f32_16x16x32_bf16 v[64:67], v[208:211], v[240:243], v[64:67]
	s_setprio 0
	s_barrier
	s_add_i32 s54, s60, s36
	v_lshl_add_u64 v[140:141], v[140:141], 0, s[48:49]
	s_mov_b32 m0, s54
	ds_read_b128 v[212:215], v154 offset:49152
	ds_read_b128 v[216:219], v154 offset:50176
	ds_read_b128 v[220:223], v154 offset:51200
	ds_read_b128 v[224:227], v154 offset:52224
	ds_read_b128 v[228:231], v154 offset:53248
	ds_read_b128 v[232:235], v154 offset:54272
	ds_read_b128 v[236:239], v154 offset:55296
	ds_read_b128 v[240:243], v154 offset:56320
	s_add_i32 m0, s54, 0x2000
	s_add_u32 s42, s42, 0x40080
	v_lshl_add_u64 v[140:141], v[180:181], 0, s[48:49]
	s_addc_u32 s43, s43, 0
	s_add_i32 s54, s61, s36
	v_lshl_add_u64 v[140:141], s[42:43], 0, v[130:131]
	s_mov_b32 m0, s54
	s_nop 0
	v_lshl_add_u64 v[140:141], s[42:43], 0, v[134:135]
	s_add_i32 m0, s54, 0x2000
	s_nop 0
	v_lshl_add_u64 v[140:141], v[190:191], 0, s[48:49]
	s_mov_b32 m0, s44
	s_nop 0
	v_lshl_add_u64 v[140:141], v[192:193], 0, s[48:49]
	s_mov_b32 m0, s45
	s_nop 0
	s_waitcnt vmcnt(0)
	s_waitcnt lgkmcnt(0)
	s_barrier
	s_setprio 1
	s_waitcnt lgkmcnt(0)
	v_mfma_f32_16x16x32_bf16 v[60:63], v[156:159], v[212:215], v[60:63]
	v_mfma_f32_16x16x32_bf16 v[56:59], v[164:167], v[212:215], v[56:59]
	v_mfma_f32_16x16x32_bf16 v[52:55], v[156:159], v[220:223], v[52:55]
	v_mfma_f32_16x16x32_bf16 v[44:47], v[164:167], v[220:223], v[44:47]
	v_mfma_f32_16x16x32_bf16 v[36:39], v[156:159], v[228:231], v[36:39]
	v_mfma_f32_16x16x32_bf16 v[28:31], v[164:167], v[228:231], v[28:31]
	v_mfma_f32_16x16x32_bf16 v[20:23], v[156:159], v[236:239], v[20:23]
	v_mfma_f32_16x16x32_bf16 v[12:15], v[164:167], v[236:239], v[12:15]
	v_mfma_f32_16x16x32_bf16 v[60:63], v[160:163], v[216:219], v[60:63]
	v_mfma_f32_16x16x32_bf16 v[56:59], v[168:171], v[216:219], v[56:59]
	v_mfma_f32_16x16x32_bf16 v[52:55], v[160:163], v[224:227], v[52:55]
	v_mfma_f32_16x16x32_bf16 v[44:47], v[168:171], v[224:227], v[44:47]
	v_mfma_f32_16x16x32_bf16 v[36:39], v[160:163], v[232:235], v[36:39]
	v_mfma_f32_16x16x32_bf16 v[28:31], v[168:171], v[232:235], v[28:31]
	v_mfma_f32_16x16x32_bf16 v[20:23], v[160:163], v[240:243], v[20:23]
	v_mfma_f32_16x16x32_bf16 v[12:15], v[168:171], v[240:243], v[12:15]
	s_setprio 0
	s_setprio 1
	v_mfma_f32_16x16x32_bf16 v[48:51], v[172:175], v[212:215], v[48:51]
	v_mfma_f32_16x16x32_bf16 v[40:43], v[204:207], v[212:215], v[40:43]
	v_mfma_f32_16x16x32_bf16 v[32:35], v[172:175], v[220:223], v[32:35]
	v_mfma_f32_16x16x32_bf16 v[24:27], v[204:207], v[220:223], v[24:27]
	v_mfma_f32_16x16x32_bf16 v[16:19], v[172:175], v[228:231], v[16:19]
	v_mfma_f32_16x16x32_bf16 v[8:11], v[204:207], v[228:231], v[8:11]
	v_mfma_f32_16x16x32_bf16 v[4:7], v[172:175], v[236:239], v[4:7]
	v_mfma_f32_16x16x32_bf16 v[0:3], v[204:207], v[236:239], v[0:3]
	v_mfma_f32_16x16x32_bf16 v[48:51], v[176:179], v[216:219], v[48:51]
	v_mfma_f32_16x16x32_bf16 v[40:43], v[208:211], v[216:219], v[40:43]
	v_mfma_f32_16x16x32_bf16 v[32:35], v[176:179], v[224:227], v[32:35]
	v_mfma_f32_16x16x32_bf16 v[24:27], v[208:211], v[224:227], v[24:27]
	v_mfma_f32_16x16x32_bf16 v[16:19], v[176:179], v[232:235], v[16:19]
	v_mfma_f32_16x16x32_bf16 v[8:11], v[208:211], v[232:235], v[8:11]
	v_mfma_f32_16x16x32_bf16 v[4:7], v[176:179], v[240:243], v[4:7]
	v_mfma_f32_16x16x32_bf16 v[0:3], v[208:211], v[240:243], v[0:3]
	s_setprio 0
	s_barrier
	s_add_i32 s59, s59, 2
	s_add_u32 s56, s56, 0x100
	s_addc_u32 s57, s57, 0
	s_add_u32 s53, s53, 0x100
	s_addc_u32 s58, s58, 0
	s_cmp_gt_u32 s59, 5
.Lpmo_after:
	s_and_b64 vcc, exec, s[10:11]
	s_cbranch_vccz .LBB0_1165
	s_barrier
